# v15 + code placement: last compute segment of every K-loop moved from 4 mod 8 to an 8-byte boundary (one s_nop ahead of its closing wait, one behind the back edge)
# speedup vs baseline: 1.0049x; 1.0024x over previous
; #define PG8_STAGE(bufoff, gbase, voff) do { _Pragma("unroll") for (int _i = 0; _i < 2; ++_i) \
;         __builtin_amdgcn_global_load_lds((const unsigned*)((const char*)(gbase) + (voff)[_i]), (LAS unsigned*)(lds + (bufoff) + ldsw + _i * 8192), 16, 0, 0); } while (0)
; #define PG8_LDA(dst, b, h) do { _Pragma("unroll") for (int m = 0; m < 4; ++m) _Pragma("unroll") for (int k = 0; k < 2; ++k) dst[m][k] = *(const LAS bf16x8*)(lds + PG8_SA(b, h) + aoff + m * 2048 + k * 1024); } while (0)
; #define PG8_LDB(dst, b, h) do { _Pragma("unroll") for (int n = 0; n < 2; ++n) _Pragma("unroll") for (int k = 0; k < 2; ++k) dst[n][k] = *(const LAS bf16x8*)(lds + PG8_SB(b, h) + boff + n * 2048 + k * 1024); } while (0)
; #define PG8_MMA(ai, bj, At, Bt) do { __builtin_amdgcn_s_setprio(1); _Pragma("unroll") for (int m = 0; m < 4; ++m) _Pragma("unroll") for (int n = 0; n < 2; ++n) _Pragma("unroll") for (int k = 0; k < 2; ++k) \
;         acc[ai][bj][m][n] = __builtin_amdgcn_mfma_f32_16x16x32_bf16(Bt[n][k], At[m][k], acc[ai][bj][m][n], 0, 0, 0); __builtin_amdgcn_s_setprio(0); } while (0)
; #define PG8_WAIT_V(n) asm volatile("s_waitcnt vmcnt(" #n ")" ::: "memory")
; #define PG8_WAIT_L(n) asm volatile("s_waitcnt lgkmcnt(" #n ")" ::: "memory")
; template <class Epi, class Sched, bool ALIGN_EPI = false, bool SP2 = false>
; __device__ __forceinline__ void gemm_phase(LAS unsigned char* lds, const Gemm g, const Sched& S, const Epi& E) {
;     ...
;         for (int t = 0; t < nt; t += 2) {
;             const bool last = (t == nt - 2);
;             const char* a1 = cA + (size_t)(t + 1) * kstep;
;             const char* a2 = last ? nA : cA + (size_t)(t + 2) * kstep; const char* b2 = last ? nB : cB + (size_t)(t + 2) * kstep;
;             const char* a3 = a2 + kstep; const char* b3 = b2 + kstep;
;             if (last && has_next) S.a_ready(nxt);
;             if constexpr (SP2) {
;             PG8_LDB(B0, 0, 0); PG8_LDB(B1, 0, 1); PG8_SCHED; PG8_LDA(At, 0, 0); PG8_STAGE(PG8_SA(1, 1), a1 + hstep, voffA);
;             PG8_WAIT_V(8); PG8_WAIT_L(0); PG8_BAR; PG8_MMA(0, 0, At, B0); PG8_MMA(0, 1, At, B1); PG8_BAR; PG8_SCHED;
;             PG8_LDA(At, 0, 1); PG8_STAGE(PG8_SB(0, 0), b2, voffB); PG8_STAGE(PG8_SB(0, 1), b2 + hstep, voffB); PG8_STAGE(PG8_SA(0, 0), a2, voffA);
;             PG8_WAIT_V(8); PG8_WAIT_L(0); PG8_BAR; PG8_MMA(1, 0, At, B0); PG8_MMA(1, 1, At, B1); PG8_BAR; PG8_SCHED;
.LBB0_260:
	s_add_i32 s44, 0, 0x10000
	s_add_i32 s48, 0, 0x14000
	v_add_u32_e32 v146, s44, v149
	ds_read_b128 v[142:145], v146
	ds_read_b128 v[156:159], v146 offset:1024
	ds_read_b128 v[160:163], v146 offset:2048
	ds_read_b128 v[164:167], v146 offset:3072
	v_add_u32_e32 v146, s48, v149
	ds_read_b128 v[168:171], v146
	ds_read_b128 v[172:175], v146 offset:1024
	ds_read_b128 v[176:179], v146 offset:2048
	ds_read_b128 v[180:183], v146 offset:3072
	ds_read_b128 v[184:187], v155
	ds_read_b128 v[188:191], v155 offset:1024
	ds_read_b128 v[198:201], v155 offset:2048
	ds_read_b128 v[202:205], v155 offset:3072
	ds_read_b128 v[206:209], v155 offset:4096
	ds_read_b128 v[210:213], v155 offset:5120
	ds_read_b128 v[214:217], v155 offset:6144
	ds_read_b128 v[228:231], v155 offset:7168
	s_add_u32 s100, s10, 0xfff00000
	s_addc_u32 s101, s11, -1
	s_add_u32 s12, s10, 0xfff00080
	s_addc_u32 s13, s11, -1
	s_cmp_eq_u32 s42, 60
	s_cselect_b32 s15, s2, s13
	s_cselect_b32 s14, s3, s12
	s_cselect_b32 s13, s17, s41
	s_cselect_b32 s12, s23, s25
	s_add_i32 m0, s34, 0xc000
	s_mov_b32 m0, s38
	s_nop 0
	global_load_lds_dwordx4 v132, s[100:101]
	s_mov_b32 m0, s39
	s_nop 0
	global_load_lds_dwordx4 v130, s[100:101]
	s_add_i32 m0, s34, 0xc000
	s_nop 0
	global_load_lds_dwordx4 v138, s[10:11]
	s_add_i32 m0, s34, 0xe000
	s_nop 0
	global_load_lds_dwordx4 v140, s[10:11]
	s_waitcnt vmcnt(8)
	s_waitcnt lgkmcnt(0)
	s_barrier
	s_setprio 1
	s_waitcnt lgkmcnt(0)
	v_mfma_f32_16x16x32_bf16 v[124:127], v[142:145], v[184:187], v[124:127]
	v_mfma_f32_16x16x32_bf16 v[120:123], v[160:163], v[184:187], v[120:123]
	v_mfma_f32_16x16x32_bf16 v[108:111], v[142:145], v[198:201], v[108:111]
	v_mfma_f32_16x16x32_bf16 v[104:107], v[160:163], v[198:201], v[104:107]
	v_mfma_f32_16x16x32_bf16 v[92:95], v[142:145], v[206:209], v[92:95]
	v_mfma_f32_16x16x32_bf16 v[88:91], v[160:163], v[206:209], v[88:91]
	v_mfma_f32_16x16x32_bf16 v[76:79], v[142:145], v[214:217], v[76:79]
	v_mfma_f32_16x16x32_bf16 v[72:75], v[160:163], v[214:217], v[72:75]
	v_mfma_f32_16x16x32_bf16 v[124:127], v[156:159], v[188:191], v[124:127]
	v_mfma_f32_16x16x32_bf16 v[120:123], v[164:167], v[188:191], v[120:123]
	v_mfma_f32_16x16x32_bf16 v[108:111], v[156:159], v[202:205], v[108:111]
	v_mfma_f32_16x16x32_bf16 v[104:107], v[164:167], v[202:205], v[104:107]
	v_mfma_f32_16x16x32_bf16 v[92:95], v[156:159], v[210:213], v[92:95]
	v_mfma_f32_16x16x32_bf16 v[88:91], v[164:167], v[210:213], v[88:91]
	v_mfma_f32_16x16x32_bf16 v[76:79], v[156:159], v[228:231], v[76:79]
	v_mfma_f32_16x16x32_bf16 v[72:75], v[164:167], v[228:231], v[72:75]
	s_setprio 0
	s_setprio 1
	v_mfma_f32_16x16x32_bf16 v[116:119], v[168:171], v[184:187], v[116:119]
	v_mfma_f32_16x16x32_bf16 v[112:115], v[176:179], v[184:187], v[112:115]
	v_mfma_f32_16x16x32_bf16 v[100:103], v[168:171], v[198:201], v[100:103]
	v_mfma_f32_16x16x32_bf16 v[96:99], v[176:179], v[198:201], v[96:99]
	v_mfma_f32_16x16x32_bf16 v[84:87], v[168:171], v[206:209], v[84:87]
	v_mfma_f32_16x16x32_bf16 v[80:83], v[176:179], v[206:209], v[80:83]
	v_mfma_f32_16x16x32_bf16 v[68:71], v[168:171], v[214:217], v[68:71]
	v_mfma_f32_16x16x32_bf16 v[64:67], v[176:179], v[214:217], v[64:67]
	v_mfma_f32_16x16x32_bf16 v[116:119], v[172:175], v[188:191], v[116:119]
	v_mfma_f32_16x16x32_bf16 v[112:115], v[180:183], v[188:191], v[112:115]
	v_mfma_f32_16x16x32_bf16 v[100:103], v[172:175], v[202:205], v[100:103]
	v_mfma_f32_16x16x32_bf16 v[96:99], v[180:183], v[202:205], v[96:99]
	v_mfma_f32_16x16x32_bf16 v[84:87], v[172:175], v[210:213], v[84:87]
	v_mfma_f32_16x16x32_bf16 v[80:83], v[180:183], v[210:213], v[80:83]
	v_mfma_f32_16x16x32_bf16 v[68:71], v[172:175], v[228:231], v[68:71]
	v_mfma_f32_16x16x32_bf16 v[64:67], v[180:183], v[228:231], v[64:67]
	s_setprio 0
	s_barrier
	ds_read_b128 v[184:187], v155 offset:16384
	ds_read_b128 v[188:191], v155 offset:17408
	ds_read_b128 v[198:201], v155 offset:18432
	ds_read_b128 v[202:205], v155 offset:19456
	ds_read_b128 v[206:209], v155 offset:20480
	ds_read_b128 v[210:213], v155 offset:21504
	ds_read_b128 v[214:217], v155 offset:22528
	ds_read_b128 v[228:231], v155 offset:23552
	s_add_u32 s98, s12, 0x80
	s_addc_u32 s99, s13, 0
	s_add_i32 s44, s44, s7
	s_mov_b32 m0, s44
	s_nop 0
	global_load_lds_dwordx4 v196, s[12:13]
	s_add_i32 m0, s44, 0x2000
	s_add_u32 s46, s12, 0x100000
	s_addc_u32 s47, s13, 0
	s_add_i32 s44, s48, s7
	global_load_lds_dwordx4 v128, s[12:13]
	s_mov_b32 m0, s44
	s_nop 0
	global_load_lds_dwordx4 v196, s[46:47]
	s_add_i32 m0, s44, 0x2000
	s_nop 0
	global_load_lds_dwordx4 v128, s[46:47]
	s_waitcnt vmcnt(6)
	s_waitcnt lgkmcnt(0)
	s_barrier
; #define PG8_STAGE(bufoff, gbase, voff) do { _Pragma("unroll") for (int _i = 0; _i < 2; ++_i) \
;         __builtin_amdgcn_global_load_lds((const unsigned*)((const char*)(gbase) + (voff)[_i]), (LAS unsigned*)(lds + (bufoff) + ldsw + _i * 8192), 16, 0, 0); } while (0)
; #define PG8_LDA(dst, b, h) do { _Pragma("unroll") for (int m = 0; m < 4; ++m) _Pragma("unroll") for (int k = 0; k < 2; ++k) dst[m][k] = *(const LAS bf16x8*)(lds + PG8_SA(b, h) + aoff + m * 2048 + k * 1024); } while (0)
; #define PG8_LDB(dst, b, h) do { _Pragma("unroll") for (int n = 0; n < 2; ++n) _Pragma("unroll") for (int k = 0; k < 2; ++k) dst[n][k] = *(const LAS bf16x8*)(lds + PG8_SB(b, h) + boff + n * 2048 + k * 1024); } while (0)
; #define PG8_MMA(ai, bj, At, Bt) do { __builtin_amdgcn_s_setprio(1); _Pragma("unroll") for (int m = 0; m < 4; ++m) _Pragma("unroll") for (int n = 0; n < 2; ++n) _Pragma("unroll") for (int k = 0; k < 2; ++k) \
;         acc[ai][bj][m][n] = __builtin_amdgcn_mfma_f32_16x16x32_bf16(Bt[n][k], At[m][k], acc[ai][bj][m][n], 0, 0, 0); __builtin_amdgcn_s_setprio(0); } while (0)
; #define PG8_WAIT_V(n) asm volatile("s_waitcnt vmcnt(" #n ")" ::: "memory")
; #define PG8_WAIT_L(n) asm volatile("s_waitcnt lgkmcnt(" #n ")" ::: "memory")
; #define PG8_BAR __builtin_amdgcn_s_barrier()
; #define PG8_SCHED __builtin_amdgcn_sched_barrier(0)
; template <class Epi, class Sched, bool ALIGN_EPI = false, bool SP2 = false>
; __device__ __forceinline__ void gemm_phase(LAS unsigned char* lds, const Gemm g, const Sched& S, const Epi& E) {
;     ...
;             PG8_WAIT_V(8); PG8_WAIT_L(0); PG8_BAR; PG8_MMA(0, 0, At, B0); PG8_MMA(0, 1, At, B1); PG8_BAR; PG8_SCHED;
;             PG8_LDA(At, 0, 1); PG8_STAGE(PG8_SB(0, 0), b2, voffB); PG8_STAGE(PG8_SB(0, 1), b2 + hstep, voffB); PG8_STAGE(PG8_SA(0, 0), a2, voffA);
;             PG8_WAIT_V(8); PG8_WAIT_L(0); PG8_BAR; PG8_MMA(1, 0, At, B0); PG8_MMA(1, 1, At, B1); PG8_BAR; PG8_SCHED;
;             PG8_LDB(B0, 1, 0); PG8_LDB(B1, 1, 1); PG8_SCHED; PG8_LDA(At, 1, 0); PG8_STAGE(PG8_SA(0, 1), a2 + hstep, voffA);
;             PG8_WAIT_V(8); PG8_WAIT_L(0); PG8_BAR; PG8_MMA(0, 0, At, B0); PG8_MMA(0, 1, At, B1); PG8_BAR; PG8_SCHED;
	s_setprio 1
	s_waitcnt lgkmcnt(0)
	v_mfma_f32_16x16x32_bf16 v[60:63], v[142:145], v[184:187], v[60:63]
	v_mfma_f32_16x16x32_bf16 v[56:59], v[160:163], v[184:187], v[56:59]
	v_mfma_f32_16x16x32_bf16 v[44:47], v[142:145], v[198:201], v[44:47]
	v_mfma_f32_16x16x32_bf16 v[40:43], v[160:163], v[198:201], v[40:43]
	v_mfma_f32_16x16x32_bf16 v[28:31], v[142:145], v[206:209], v[28:31]
	v_mfma_f32_16x16x32_bf16 v[24:27], v[160:163], v[206:209], v[24:27]
	v_mfma_f32_16x16x32_bf16 v[12:15], v[142:145], v[214:217], v[12:15]
	v_mfma_f32_16x16x32_bf16 v[8:11], v[160:163], v[214:217], v[8:11]
	v_mfma_f32_16x16x32_bf16 v[60:63], v[156:159], v[188:191], v[60:63]
	v_mfma_f32_16x16x32_bf16 v[56:59], v[164:167], v[188:191], v[56:59]
	v_mfma_f32_16x16x32_bf16 v[44:47], v[156:159], v[202:205], v[44:47]
	v_mfma_f32_16x16x32_bf16 v[40:43], v[164:167], v[202:205], v[40:43]
	v_mfma_f32_16x16x32_bf16 v[28:31], v[156:159], v[210:213], v[28:31]
	v_mfma_f32_16x16x32_bf16 v[24:27], v[164:167], v[210:213], v[24:27]
	v_mfma_f32_16x16x32_bf16 v[12:15], v[156:159], v[228:231], v[12:15]
	v_mfma_f32_16x16x32_bf16 v[8:11], v[164:167], v[228:231], v[8:11]
	s_setprio 0
	s_setprio 1
	v_mfma_f32_16x16x32_bf16 v[52:55], v[168:171], v[184:187], v[52:55]
	v_mfma_f32_16x16x32_bf16 v[48:51], v[176:179], v[184:187], v[48:51]
	v_mfma_f32_16x16x32_bf16 v[36:39], v[168:171], v[198:201], v[36:39]
	v_mfma_f32_16x16x32_bf16 v[32:35], v[176:179], v[198:201], v[32:35]
	v_mfma_f32_16x16x32_bf16 v[20:23], v[168:171], v[206:209], v[20:23]
	v_mfma_f32_16x16x32_bf16 v[16:19], v[176:179], v[206:209], v[16:19]
	v_mfma_f32_16x16x32_bf16 v[4:7], v[168:171], v[214:217], v[4:7]
	v_mfma_f32_16x16x32_bf16 v[0:3], v[176:179], v[214:217], v[0:3]
	v_mfma_f32_16x16x32_bf16 v[52:55], v[172:175], v[188:191], v[52:55]
	v_mfma_f32_16x16x32_bf16 v[48:51], v[180:183], v[188:191], v[48:51]
	v_mfma_f32_16x16x32_bf16 v[36:39], v[172:175], v[202:205], v[36:39]
	v_mfma_f32_16x16x32_bf16 v[32:35], v[180:183], v[202:205], v[32:35]
	v_mfma_f32_16x16x32_bf16 v[20:23], v[172:175], v[210:213], v[20:23]
	v_mfma_f32_16x16x32_bf16 v[16:19], v[180:183], v[210:213], v[16:19]
	v_mfma_f32_16x16x32_bf16 v[4:7], v[172:175], v[228:231], v[4:7]
	v_mfma_f32_16x16x32_bf16 v[0:3], v[180:183], v[228:231], v[0:3]
	s_setprio 0
	s_barrier
	s_add_i32 s44, 0, 0x18000
	s_add_i32 s46, 0, 0x1c000
	v_add_u32_e32 v164, s44, v149
	v_add_u32_e32 v180, s46, v149
	ds_read_b128 v[142:145], v164
	ds_read_b128 v[156:159], v164 offset:1024
	ds_read_b128 v[160:163], v164 offset:2048
	ds_read_b128 v[164:167], v164 offset:3072
	ds_read_b128 v[168:171], v180
	ds_read_b128 v[172:175], v180 offset:1024
	ds_read_b128 v[176:179], v180 offset:2048
	ds_read_b128 v[180:183], v180 offset:3072
	ds_read_b128 v[184:187], v155 offset:32768
	ds_read_b128 v[188:191], v155 offset:33792
	ds_read_b128 v[198:201], v155 offset:34816
	ds_read_b128 v[202:205], v155 offset:35840
	ds_read_b128 v[206:209], v155 offset:36864
	ds_read_b128 v[210:213], v155 offset:37888
	ds_read_b128 v[214:217], v155 offset:38912
	ds_read_b128 v[228:231], v155 offset:39936
	s_mov_b32 m0, s34
	s_nop 0
	global_load_lds_dwordx4 v132, s[14:15]
	s_mov_b32 m0, s35
	s_nop 0
	global_load_lds_dwordx4 v130, s[14:15]
	s_add_u32 s14, s14, 0x100000
	s_addc_u32 s15, s15, 0
	s_mov_b32 m0, s36
	s_nop 0
	global_load_lds_dwordx4 v132, s[14:15]
	s_mov_b32 m0, s37
	s_nop 0
	global_load_lds_dwordx4 v130, s[14:15]
	s_waitcnt vmcnt(8)
	s_waitcnt lgkmcnt(0)
	s_barrier
; #define PG8_STAGE(bufoff, gbase, voff) do { _Pragma("unroll") for (int _i = 0; _i < 2; ++_i) \
;         __builtin_amdgcn_global_load_lds((const unsigned*)((const char*)(gbase) + (voff)[_i]), (LAS unsigned*)(lds + (bufoff) + ldsw + _i * 8192), 16, 0, 0); } while (0)
; #define PG8_LDA(dst, b, h) do { _Pragma("unroll") for (int m = 0; m < 4; ++m) _Pragma("unroll") for (int k = 0; k < 2; ++k) dst[m][k] = *(const LAS bf16x8*)(lds + PG8_SA(b, h) + aoff + m * 2048 + k * 1024); } while (0)
; #define PG8_MMA(ai, bj, At, Bt) do { __builtin_amdgcn_s_setprio(1); _Pragma("unroll") for (int m = 0; m < 4; ++m) _Pragma("unroll") for (int n = 0; n < 2; ++n) _Pragma("unroll") for (int k = 0; k < 2; ++k) \
;         acc[ai][bj][m][n] = __builtin_amdgcn_mfma_f32_16x16x32_bf16(Bt[n][k], At[m][k], acc[ai][bj][m][n], 0, 0, 0); __builtin_amdgcn_s_setprio(0); } while (0)
; #define PG8_WAIT_V(n) asm volatile("s_waitcnt vmcnt(" #n ")" ::: "memory")
; #define PG8_WAIT_L(n) asm volatile("s_waitcnt lgkmcnt(" #n ")" ::: "memory")
; #define PG8_BAR __builtin_amdgcn_s_barrier()
; #define PG8_SCHED __builtin_amdgcn_sched_barrier(0)
; template <class Epi, class Sched, bool ALIGN_EPI = false, bool SP2 = false>
; __device__ __forceinline__ void gemm_phase(LAS unsigned char* lds, const Gemm g, const Sched& S, const Epi& E) {
;     ...
;         for (int t = 0; t < nt; t += 2) {
;     ...
;             PG8_WAIT_V(8); PG8_WAIT_L(0); PG8_BAR; PG8_MMA(0, 0, At, B0); PG8_MMA(0, 1, At, B1); PG8_BAR; PG8_SCHED;
;             PG8_LDA(At, 1, 1); PG8_STAGE(PG8_SB(1, 0), b3, voffB); PG8_STAGE(PG8_SB(1, 1), b3 + hstep, voffB); PG8_STAGE(PG8_SA(1, 0), a3, voffA);
;             PG8_WAIT_V(8); PG8_WAIT_L(0); PG8_BAR; PG8_MMA(1, 0, At, B0); PG8_MMA(1, 1, At, B1); PG8_BAR; PG8_SCHED;
;     ...
;         if constexpr (ALIGN_EPI) { if (wr == 0) PG8_BAR; }
	s_setprio 1
	s_waitcnt lgkmcnt(0)
	v_mfma_f32_16x16x32_bf16 v[124:127], v[142:145], v[184:187], v[124:127]
	v_mfma_f32_16x16x32_bf16 v[120:123], v[160:163], v[184:187], v[120:123]
	v_mfma_f32_16x16x32_bf16 v[108:111], v[142:145], v[198:201], v[108:111]
	v_mfma_f32_16x16x32_bf16 v[104:107], v[160:163], v[198:201], v[104:107]
	v_mfma_f32_16x16x32_bf16 v[92:95], v[142:145], v[206:209], v[92:95]
	v_mfma_f32_16x16x32_bf16 v[88:91], v[160:163], v[206:209], v[88:91]
	v_mfma_f32_16x16x32_bf16 v[76:79], v[142:145], v[214:217], v[76:79]
	v_mfma_f32_16x16x32_bf16 v[72:75], v[160:163], v[214:217], v[72:75]
	v_mfma_f32_16x16x32_bf16 v[124:127], v[156:159], v[188:191], v[124:127]
	v_mfma_f32_16x16x32_bf16 v[120:123], v[164:167], v[188:191], v[120:123]
	v_mfma_f32_16x16x32_bf16 v[108:111], v[156:159], v[202:205], v[108:111]
	v_mfma_f32_16x16x32_bf16 v[104:107], v[164:167], v[202:205], v[104:107]
	v_mfma_f32_16x16x32_bf16 v[92:95], v[156:159], v[210:213], v[92:95]
	v_mfma_f32_16x16x32_bf16 v[88:91], v[164:167], v[210:213], v[88:91]
	v_mfma_f32_16x16x32_bf16 v[76:79], v[156:159], v[228:231], v[76:79]
	v_mfma_f32_16x16x32_bf16 v[72:75], v[164:167], v[228:231], v[72:75]
	s_setprio 0
	s_setprio 1
	v_mfma_f32_16x16x32_bf16 v[116:119], v[168:171], v[184:187], v[116:119]
	v_mfma_f32_16x16x32_bf16 v[112:115], v[176:179], v[184:187], v[112:115]
	v_mfma_f32_16x16x32_bf16 v[100:103], v[168:171], v[198:201], v[100:103]
	v_mfma_f32_16x16x32_bf16 v[96:99], v[176:179], v[198:201], v[96:99]
	v_mfma_f32_16x16x32_bf16 v[84:87], v[168:171], v[206:209], v[84:87]
	v_mfma_f32_16x16x32_bf16 v[80:83], v[176:179], v[206:209], v[80:83]
	v_mfma_f32_16x16x32_bf16 v[68:71], v[168:171], v[214:217], v[68:71]
	v_mfma_f32_16x16x32_bf16 v[64:67], v[176:179], v[214:217], v[64:67]
	v_mfma_f32_16x16x32_bf16 v[116:119], v[172:175], v[188:191], v[116:119]
	v_mfma_f32_16x16x32_bf16 v[112:115], v[180:183], v[188:191], v[112:115]
	v_mfma_f32_16x16x32_bf16 v[100:103], v[172:175], v[202:205], v[100:103]
	v_mfma_f32_16x16x32_bf16 v[96:99], v[180:183], v[202:205], v[96:99]
	v_mfma_f32_16x16x32_bf16 v[84:87], v[172:175], v[210:213], v[84:87]
	v_mfma_f32_16x16x32_bf16 v[80:83], v[180:183], v[210:213], v[80:83]
	v_mfma_f32_16x16x32_bf16 v[68:71], v[172:175], v[228:231], v[68:71]
	v_mfma_f32_16x16x32_bf16 v[64:67], v[180:183], v[228:231], v[64:67]
	s_setprio 0
	s_barrier
	ds_read_b128 v[184:187], v155 offset:49152
	ds_read_b128 v[188:191], v155 offset:50176
	ds_read_b128 v[198:201], v155 offset:51200
	ds_read_b128 v[202:205], v155 offset:52224
	ds_read_b128 v[206:209], v155 offset:53248
	ds_read_b128 v[210:213], v155 offset:54272
	ds_read_b128 v[214:217], v155 offset:55296
	ds_read_b128 v[228:231], v155 offset:56320
	s_add_i32 s14, s44, s7
	s_mov_b32 m0, s14
	s_nop 0
	global_load_lds_dwordx4 v196, s[98:99]
	s_add_i32 m0, s14, 0x2000
	s_add_u32 s12, s12, 0x100080
	s_addc_u32 s13, s13, 0
	s_add_i32 s14, s46, s7
	global_load_lds_dwordx4 v128, s[98:99]
	s_mov_b32 m0, s14
	s_nop 0
	global_load_lds_dwordx4 v196, s[12:13]
	s_add_i32 m0, s14, 0x2000
	s_nop 0
	global_load_lds_dwordx4 v128, s[12:13]
	s_nop 0
	s_waitcnt vmcnt(6)
	s_waitcnt lgkmcnt(0)
	s_barrier
	s_setprio 1
	s_waitcnt lgkmcnt(0)
	v_mfma_f32_16x16x32_bf16 v[60:63], v[142:145], v[184:187], v[60:63]
	v_mfma_f32_16x16x32_bf16 v[56:59], v[160:163], v[184:187], v[56:59]
	v_mfma_f32_16x16x32_bf16 v[44:47], v[142:145], v[198:201], v[44:47]
	v_mfma_f32_16x16x32_bf16 v[40:43], v[160:163], v[198:201], v[40:43]
	v_mfma_f32_16x16x32_bf16 v[28:31], v[142:145], v[206:209], v[28:31]
	v_mfma_f32_16x16x32_bf16 v[24:27], v[160:163], v[206:209], v[24:27]
	v_mfma_f32_16x16x32_bf16 v[12:15], v[142:145], v[214:217], v[12:15]
	v_mfma_f32_16x16x32_bf16 v[8:11], v[160:163], v[214:217], v[8:11]
	v_mfma_f32_16x16x32_bf16 v[60:63], v[156:159], v[188:191], v[60:63]
	v_mfma_f32_16x16x32_bf16 v[56:59], v[164:167], v[188:191], v[56:59]
	v_mfma_f32_16x16x32_bf16 v[44:47], v[156:159], v[202:205], v[44:47]
	v_mfma_f32_16x16x32_bf16 v[40:43], v[164:167], v[202:205], v[40:43]
	v_mfma_f32_16x16x32_bf16 v[28:31], v[156:159], v[210:213], v[28:31]
	v_mfma_f32_16x16x32_bf16 v[24:27], v[164:167], v[210:213], v[24:27]
	v_mfma_f32_16x16x32_bf16 v[12:15], v[156:159], v[228:231], v[12:15]
	v_mfma_f32_16x16x32_bf16 v[8:11], v[164:167], v[228:231], v[8:11]
	s_setprio 0
	s_setprio 1
	v_mfma_f32_16x16x32_bf16 v[52:55], v[168:171], v[184:187], v[52:55]
	v_mfma_f32_16x16x32_bf16 v[48:51], v[176:179], v[184:187], v[48:51]
	v_mfma_f32_16x16x32_bf16 v[36:39], v[168:171], v[198:201], v[36:39]
	v_mfma_f32_16x16x32_bf16 v[32:35], v[176:179], v[198:201], v[32:35]
	v_mfma_f32_16x16x32_bf16 v[20:23], v[168:171], v[206:209], v[20:23]
	v_mfma_f32_16x16x32_bf16 v[16:19], v[176:179], v[206:209], v[16:19]
	v_mfma_f32_16x16x32_bf16 v[4:7], v[168:171], v[214:217], v[4:7]
	v_mfma_f32_16x16x32_bf16 v[0:3], v[176:179], v[214:217], v[0:3]
	v_mfma_f32_16x16x32_bf16 v[52:55], v[172:175], v[188:191], v[52:55]
	v_mfma_f32_16x16x32_bf16 v[48:51], v[180:183], v[188:191], v[48:51]
	v_mfma_f32_16x16x32_bf16 v[36:39], v[172:175], v[202:205], v[36:39]
	v_mfma_f32_16x16x32_bf16 v[32:35], v[180:183], v[202:205], v[32:35]
	v_mfma_f32_16x16x32_bf16 v[20:23], v[172:175], v[210:213], v[20:23]
	v_mfma_f32_16x16x32_bf16 v[16:19], v[180:183], v[210:213], v[16:19]
	v_mfma_f32_16x16x32_bf16 v[4:7], v[172:175], v[228:231], v[4:7]
	v_mfma_f32_16x16x32_bf16 v[0:3], v[180:183], v[228:231], v[0:3]
	s_setprio 0
	s_barrier
	s_add_i32 s42, s42, 2
	s_add_u32 s10, s10, 0x100
	s_addc_u32 s11, s11, 0
	s_add_u32 s25, s25, 0x100
	s_addc_u32 s41, s41, 0
	s_cmp_gt_u32 s42, 61
	s_cbranch_scc0 .LBB0_260
	s_nop 0
	s_and_b64 vcc, exec, s[20:21]
	s_cbranch_vccz .LBB0_263
	s_barrier

; #define PG8_STAGE(bufoff, gbase, voff) do { _Pragma("unroll") for (int _i = 0; _i < 2; ++_i) \
;         __builtin_amdgcn_global_load_lds((const unsigned*)((const char*)(gbase) + (voff)[_i]), (LAS unsigned*)(lds + (bufoff) + ldsw + _i * 8192), 16, 0, 0); } while (0)
; #define PG8_LDA(dst, b, h) do { _Pragma("unroll") for (int m = 0; m < 4; ++m) _Pragma("unroll") for (int k = 0; k < 2; ++k) dst[m][k] = *(const LAS bf16x8*)(lds + PG8_SA(b, h) + aoff + m * 2048 + k * 1024); } while (0)
; #define PG8_LDB(dst, b, h) do { _Pragma("unroll") for (int n = 0; n < 2; ++n) _Pragma("unroll") for (int k = 0; k < 2; ++k) dst[n][k] = *(const LAS bf16x8*)(lds + PG8_SB(b, h) + boff + n * 2048 + k * 1024); } while (0)
; #define PG8_MMA(ai, bj, At, Bt) do { __builtin_amdgcn_s_setprio(1); _Pragma("unroll") for (int m = 0; m < 4; ++m) _Pragma("unroll") for (int n = 0; n < 2; ++n) _Pragma("unroll") for (int k = 0; k < 2; ++k) \
;         acc[ai][bj][m][n] = __builtin_amdgcn_mfma_f32_16x16x32_bf16(Bt[n][k], At[m][k], acc[ai][bj][m][n], 0, 0, 0); __builtin_amdgcn_s_setprio(0); } while (0)
; #define PG8_WAIT_V(n) asm volatile("s_waitcnt vmcnt(" #n ")" ::: "memory")
; #define PG8_WAIT_L(n) asm volatile("s_waitcnt lgkmcnt(" #n ")" ::: "memory")
; #define PG8_BAR __builtin_amdgcn_s_barrier()
; template <class Epi, class Sched, bool ALIGN_EPI = false, bool SP2 = false>
; __device__ __forceinline__ void gemm_phase(LAS unsigned char* lds, const Gemm g, const Sched& S, const Epi& E) {
;     ...
;             const bool last = (t == nt - 2);
;             const char* a1 = cA + (size_t)(t + 1) * kstep;
;             const char* a2 = last ? nA : cA + (size_t)(t + 2) * kstep; const char* b2 = last ? nB : cB + (size_t)(t + 2) * kstep;
;             const char* a3 = a2 + kstep; const char* b3 = b2 + kstep;
;             if (last && has_next) S.a_ready(nxt);
;             if constexpr (SP2) {
;             PG8_LDB(B0, 0, 0); PG8_LDB(B1, 0, 1); PG8_SCHED; PG8_LDA(At, 0, 0); PG8_STAGE(PG8_SA(1, 1), a1 + hstep, voffA);
;             PG8_WAIT_V(8); PG8_WAIT_L(0); PG8_BAR; PG8_MMA(0, 0, At, B0); PG8_MMA(0, 1, At, B1); PG8_BAR; PG8_SCHED;
;             PG8_LDA(At, 0, 1); PG8_STAGE(PG8_SB(0, 0), b2, voffB); PG8_STAGE(PG8_SB(0, 1), b2 + hstep, voffB); PG8_STAGE(PG8_SA(0, 0), a2, voffA);
;             PG8_WAIT_V(8); PG8_WAIT_L(0); PG8_BAR; PG8_MMA(1, 0, At, B0); PG8_MMA(1, 1, At, B1); PG8_BAR; PG8_SCHED;
.LBB0_424:
	s_add_i32 s48, 0, 0x10000
	s_add_i32 s90, 0, 0x14000
	v_add_u32_e32 v146, s48, v149
	ds_read_b128 v[142:145], v146
	ds_read_b128 v[156:159], v146 offset:1024
	ds_read_b128 v[160:163], v146 offset:2048
	ds_read_b128 v[164:167], v146 offset:3072
	v_add_u32_e32 v146, s90, v149
	ds_read_b128 v[168:171], v146
	ds_read_b128 v[172:175], v146 offset:1024
	ds_read_b128 v[176:179], v146 offset:2048
	ds_read_b128 v[180:183], v146 offset:3072
	ds_read_b128 v[184:187], v155
	ds_read_b128 v[188:191], v155 offset:1024
	ds_read_b128 v[198:201], v155 offset:2048
	ds_read_b128 v[202:205], v155 offset:3072
	ds_read_b128 v[206:209], v155 offset:4096
	ds_read_b128 v[210:213], v155 offset:5120
	ds_read_b128 v[214:217], v155 offset:6144
	ds_read_b128 v[228:231], v155 offset:7168
	s_add_u32 s100, s10, 0xfff00000
	s_addc_u32 s101, s11, -1
	s_add_u32 s12, s10, 0xfff00080
	s_addc_u32 s13, s11, -1
	s_cmp_eq_u32 s42, 60
	s_cselect_b32 s15, s2, s13
	s_cselect_b32 s14, s3, s12
	s_cselect_b32 s13, s17, s41
	s_cselect_b32 s12, s23, s25
	s_add_i32 m0, s34, 0xc000
	s_mov_b32 m0, s38
	s_nop 0
	global_load_lds_dwordx4 v128, s[100:101]
	s_mov_b32 m0, s39
	s_nop 0
	global_load_lds_dwordx4 v130, s[100:101]
	s_add_i32 m0, s34, 0xc000
	s_nop 0
	global_load_lds_dwordx4 v138, s[10:11]
	s_add_i32 m0, s34, 0xe000
	s_nop 0
	global_load_lds_dwordx4 v140, s[10:11]
	s_waitcnt vmcnt(8)
	s_waitcnt lgkmcnt(0)
	s_barrier
	s_setprio 1
	s_waitcnt lgkmcnt(0)
	v_mfma_f32_16x16x32_bf16 v[124:127], v[142:145], v[184:187], v[124:127]
	v_mfma_f32_16x16x32_bf16 v[120:123], v[160:163], v[184:187], v[120:123]
	v_mfma_f32_16x16x32_bf16 v[108:111], v[142:145], v[198:201], v[108:111]
	v_mfma_f32_16x16x32_bf16 v[104:107], v[160:163], v[198:201], v[104:107]
	v_mfma_f32_16x16x32_bf16 v[92:95], v[142:145], v[206:209], v[92:95]
	v_mfma_f32_16x16x32_bf16 v[88:91], v[160:163], v[206:209], v[88:91]
	v_mfma_f32_16x16x32_bf16 v[76:79], v[142:145], v[214:217], v[76:79]
	v_mfma_f32_16x16x32_bf16 v[72:75], v[160:163], v[214:217], v[72:75]
	v_mfma_f32_16x16x32_bf16 v[124:127], v[156:159], v[188:191], v[124:127]
	v_mfma_f32_16x16x32_bf16 v[120:123], v[164:167], v[188:191], v[120:123]
	v_mfma_f32_16x16x32_bf16 v[108:111], v[156:159], v[202:205], v[108:111]
	v_mfma_f32_16x16x32_bf16 v[104:107], v[164:167], v[202:205], v[104:107]
	v_mfma_f32_16x16x32_bf16 v[92:95], v[156:159], v[210:213], v[92:95]
	v_mfma_f32_16x16x32_bf16 v[88:91], v[164:167], v[210:213], v[88:91]
	v_mfma_f32_16x16x32_bf16 v[76:79], v[156:159], v[228:231], v[76:79]
	v_mfma_f32_16x16x32_bf16 v[72:75], v[164:167], v[228:231], v[72:75]
	s_setprio 0
	s_setprio 1
	v_mfma_f32_16x16x32_bf16 v[116:119], v[168:171], v[184:187], v[116:119]
	v_mfma_f32_16x16x32_bf16 v[112:115], v[176:179], v[184:187], v[112:115]
	v_mfma_f32_16x16x32_bf16 v[100:103], v[168:171], v[198:201], v[100:103]
	v_mfma_f32_16x16x32_bf16 v[96:99], v[176:179], v[198:201], v[96:99]
	v_mfma_f32_16x16x32_bf16 v[84:87], v[168:171], v[206:209], v[84:87]
	v_mfma_f32_16x16x32_bf16 v[80:83], v[176:179], v[206:209], v[80:83]
	v_mfma_f32_16x16x32_bf16 v[68:71], v[168:171], v[214:217], v[68:71]
	v_mfma_f32_16x16x32_bf16 v[64:67], v[176:179], v[214:217], v[64:67]
	v_mfma_f32_16x16x32_bf16 v[116:119], v[172:175], v[188:191], v[116:119]
	v_mfma_f32_16x16x32_bf16 v[112:115], v[180:183], v[188:191], v[112:115]
	v_mfma_f32_16x16x32_bf16 v[100:103], v[172:175], v[202:205], v[100:103]
	v_mfma_f32_16x16x32_bf16 v[96:99], v[180:183], v[202:205], v[96:99]
	v_mfma_f32_16x16x32_bf16 v[84:87], v[172:175], v[210:213], v[84:87]
	v_mfma_f32_16x16x32_bf16 v[80:83], v[180:183], v[210:213], v[80:83]
	v_mfma_f32_16x16x32_bf16 v[68:71], v[172:175], v[228:231], v[68:71]
	v_mfma_f32_16x16x32_bf16 v[64:67], v[180:183], v[228:231], v[64:67]
	s_setprio 0
	s_barrier
	ds_read_b128 v[184:187], v155 offset:16384
	ds_read_b128 v[188:191], v155 offset:17408
	ds_read_b128 v[198:201], v155 offset:18432
	ds_read_b128 v[202:205], v155 offset:19456
	ds_read_b128 v[206:209], v155 offset:20480
	ds_read_b128 v[210:213], v155 offset:21504
	ds_read_b128 v[214:217], v155 offset:22528
	ds_read_b128 v[228:231], v155 offset:23552
	s_add_u32 s98, s12, 0x80
	s_addc_u32 s99, s13, 0
	s_add_i32 s44, s48, s7
	s_mov_b32 m0, s44
	s_nop 0
	global_load_lds_dwordx4 v196, s[12:13]
	s_add_i32 m0, s44, 0x2000
	s_add_u32 s46, s12, 0x100000
	s_addc_u32 s47, s13, 0
	s_add_i32 s44, s90, s7
	global_load_lds_dwordx4 v132, s[12:13]
	s_mov_b32 m0, s44
	s_nop 0
	global_load_lds_dwordx4 v196, s[46:47]
	s_add_i32 m0, s44, 0x2000
	s_nop 0
	global_load_lds_dwordx4 v132, s[46:47]
	s_waitcnt vmcnt(6)
	s_waitcnt lgkmcnt(0)
	s_barrier
; #define PG8_STAGE(bufoff, gbase, voff) do { _Pragma("unroll") for (int _i = 0; _i < 2; ++_i) \
;         __builtin_amdgcn_global_load_lds((const unsigned*)((const char*)(gbase) + (voff)[_i]), (LAS unsigned*)(lds + (bufoff) + ldsw + _i * 8192), 16, 0, 0); } while (0)
; #define PG8_LDA(dst, b, h) do { _Pragma("unroll") for (int m = 0; m < 4; ++m) _Pragma("unroll") for (int k = 0; k < 2; ++k) dst[m][k] = *(const LAS bf16x8*)(lds + PG8_SA(b, h) + aoff + m * 2048 + k * 1024); } while (0)
; #define PG8_LDB(dst, b, h) do { _Pragma("unroll") for (int n = 0; n < 2; ++n) _Pragma("unroll") for (int k = 0; k < 2; ++k) dst[n][k] = *(const LAS bf16x8*)(lds + PG8_SB(b, h) + boff + n * 2048 + k * 1024); } while (0)
; #define PG8_MMA(ai, bj, At, Bt) do { __builtin_amdgcn_s_setprio(1); _Pragma("unroll") for (int m = 0; m < 4; ++m) _Pragma("unroll") for (int n = 0; n < 2; ++n) _Pragma("unroll") for (int k = 0; k < 2; ++k) \
;         acc[ai][bj][m][n] = __builtin_amdgcn_mfma_f32_16x16x32_bf16(Bt[n][k], At[m][k], acc[ai][bj][m][n], 0, 0, 0); __builtin_amdgcn_s_setprio(0); } while (0)
; #define PG8_WAIT_V(n) asm volatile("s_waitcnt vmcnt(" #n ")" ::: "memory")
; #define PG8_WAIT_L(n) asm volatile("s_waitcnt lgkmcnt(" #n ")" ::: "memory")
; #define PG8_BAR __builtin_amdgcn_s_barrier()
; #define PG8_SCHED __builtin_amdgcn_sched_barrier(0)
; template <class Epi, class Sched, bool ALIGN_EPI = false, bool SP2 = false>
; __device__ __forceinline__ void gemm_phase(LAS unsigned char* lds, const Gemm g, const Sched& S, const Epi& E) {
;     ...
;             PG8_WAIT_V(8); PG8_WAIT_L(0); PG8_BAR; PG8_MMA(1, 0, At, B0); PG8_MMA(1, 1, At, B1); PG8_BAR; PG8_SCHED;
;             PG8_LDB(B0, 1, 0); PG8_LDB(B1, 1, 1); PG8_SCHED; PG8_LDA(At, 1, 0); PG8_STAGE(PG8_SA(0, 1), a2 + hstep, voffA);
;             PG8_WAIT_V(8); PG8_WAIT_L(0); PG8_BAR; PG8_MMA(0, 0, At, B0); PG8_MMA(0, 1, At, B1); PG8_BAR; PG8_SCHED;
	s_setprio 1
	s_waitcnt lgkmcnt(0)
	v_mfma_f32_16x16x32_bf16 v[60:63], v[142:145], v[184:187], v[60:63]
	v_mfma_f32_16x16x32_bf16 v[56:59], v[160:163], v[184:187], v[56:59]
	v_mfma_f32_16x16x32_bf16 v[44:47], v[142:145], v[198:201], v[44:47]
	v_mfma_f32_16x16x32_bf16 v[40:43], v[160:163], v[198:201], v[40:43]
	v_mfma_f32_16x16x32_bf16 v[28:31], v[142:145], v[206:209], v[28:31]
	v_mfma_f32_16x16x32_bf16 v[24:27], v[160:163], v[206:209], v[24:27]
	v_mfma_f32_16x16x32_bf16 v[12:15], v[142:145], v[214:217], v[12:15]
	v_mfma_f32_16x16x32_bf16 v[8:11], v[160:163], v[214:217], v[8:11]
	v_mfma_f32_16x16x32_bf16 v[60:63], v[156:159], v[188:191], v[60:63]
	v_mfma_f32_16x16x32_bf16 v[56:59], v[164:167], v[188:191], v[56:59]
	v_mfma_f32_16x16x32_bf16 v[44:47], v[156:159], v[202:205], v[44:47]
	v_mfma_f32_16x16x32_bf16 v[40:43], v[164:167], v[202:205], v[40:43]
	v_mfma_f32_16x16x32_bf16 v[28:31], v[156:159], v[210:213], v[28:31]
	v_mfma_f32_16x16x32_bf16 v[24:27], v[164:167], v[210:213], v[24:27]
	v_mfma_f32_16x16x32_bf16 v[12:15], v[156:159], v[228:231], v[12:15]
	v_mfma_f32_16x16x32_bf16 v[8:11], v[164:167], v[228:231], v[8:11]
	s_setprio 0
	s_setprio 1
	v_mfma_f32_16x16x32_bf16 v[52:55], v[168:171], v[184:187], v[52:55]
	v_mfma_f32_16x16x32_bf16 v[48:51], v[176:179], v[184:187], v[48:51]
	v_mfma_f32_16x16x32_bf16 v[36:39], v[168:171], v[198:201], v[36:39]
	v_mfma_f32_16x16x32_bf16 v[32:35], v[176:179], v[198:201], v[32:35]
	v_mfma_f32_16x16x32_bf16 v[20:23], v[168:171], v[206:209], v[20:23]
	v_mfma_f32_16x16x32_bf16 v[16:19], v[176:179], v[206:209], v[16:19]
	v_mfma_f32_16x16x32_bf16 v[4:7], v[168:171], v[214:217], v[4:7]
	v_mfma_f32_16x16x32_bf16 v[0:3], v[176:179], v[214:217], v[0:3]
	v_mfma_f32_16x16x32_bf16 v[52:55], v[172:175], v[188:191], v[52:55]
	v_mfma_f32_16x16x32_bf16 v[48:51], v[180:183], v[188:191], v[48:51]
	v_mfma_f32_16x16x32_bf16 v[36:39], v[172:175], v[202:205], v[36:39]
	v_mfma_f32_16x16x32_bf16 v[32:35], v[180:183], v[202:205], v[32:35]
	v_mfma_f32_16x16x32_bf16 v[20:23], v[172:175], v[210:213], v[20:23]
	v_mfma_f32_16x16x32_bf16 v[16:19], v[180:183], v[210:213], v[16:19]
	v_mfma_f32_16x16x32_bf16 v[4:7], v[172:175], v[228:231], v[4:7]
	v_mfma_f32_16x16x32_bf16 v[0:3], v[180:183], v[228:231], v[0:3]
	s_setprio 0
	s_barrier
	s_add_i32 s91, 0, 0x18000
	s_add_i32 s58, 0, 0x1c000
	v_add_u32_e32 v164, s91, v149
	v_add_u32_e32 v180, s58, v149
	ds_read_b128 v[142:145], v164
	ds_read_b128 v[156:159], v164 offset:1024
	ds_read_b128 v[160:163], v164 offset:2048
	ds_read_b128 v[164:167], v164 offset:3072
	ds_read_b128 v[168:171], v180
	ds_read_b128 v[172:175], v180 offset:1024
	ds_read_b128 v[176:179], v180 offset:2048
	ds_read_b128 v[180:183], v180 offset:3072
	ds_read_b128 v[184:187], v155 offset:32768
	ds_read_b128 v[188:191], v155 offset:33792
	ds_read_b128 v[198:201], v155 offset:34816
	ds_read_b128 v[202:205], v155 offset:35840
	ds_read_b128 v[206:209], v155 offset:36864
	ds_read_b128 v[210:213], v155 offset:37888
	ds_read_b128 v[214:217], v155 offset:38912
	ds_read_b128 v[228:231], v155 offset:39936
	s_mov_b32 m0, s34
	s_nop 0
	global_load_lds_dwordx4 v128, s[14:15]
	s_mov_b32 m0, s35
	s_nop 0
	global_load_lds_dwordx4 v130, s[14:15]
	s_add_u32 s14, s14, 0x100000
	s_addc_u32 s15, s15, 0
	s_mov_b32 m0, s36
	s_nop 0
	global_load_lds_dwordx4 v128, s[14:15]
	s_mov_b32 m0, s37
	s_nop 0
	global_load_lds_dwordx4 v130, s[14:15]
	s_waitcnt vmcnt(8)
	s_waitcnt lgkmcnt(0)
	s_barrier
; #define PG8_STAGE(bufoff, gbase, voff) do { _Pragma("unroll") for (int _i = 0; _i < 2; ++_i) \
;         __builtin_amdgcn_global_load_lds((const unsigned*)((const char*)(gbase) + (voff)[_i]), (LAS unsigned*)(lds + (bufoff) + ldsw + _i * 8192), 16, 0, 0); } while (0)
; #define PG8_LDA(dst, b, h) do { _Pragma("unroll") for (int m = 0; m < 4; ++m) _Pragma("unroll") for (int k = 0; k < 2; ++k) dst[m][k] = *(const LAS bf16x8*)(lds + PG8_SA(b, h) + aoff + m * 2048 + k * 1024); } while (0)
; #define PG8_MMA(ai, bj, At, Bt) do { __builtin_amdgcn_s_setprio(1); _Pragma("unroll") for (int m = 0; m < 4; ++m) _Pragma("unroll") for (int n = 0; n < 2; ++n) _Pragma("unroll") for (int k = 0; k < 2; ++k) \
;         acc[ai][bj][m][n] = __builtin_amdgcn_mfma_f32_16x16x32_bf16(Bt[n][k], At[m][k], acc[ai][bj][m][n], 0, 0, 0); __builtin_amdgcn_s_setprio(0); } while (0)
; #define PG8_WAIT_V(n) asm volatile("s_waitcnt vmcnt(" #n ")" ::: "memory")
; #define PG8_WAIT_L(n) asm volatile("s_waitcnt lgkmcnt(" #n ")" ::: "memory")
; #define PG8_BAR __builtin_amdgcn_s_barrier()
; #define PG8_SCHED __builtin_amdgcn_sched_barrier(0)
; template <class Epi, class Sched, bool ALIGN_EPI = false, bool SP2 = false>
; __device__ __forceinline__ void gemm_phase(LAS unsigned char* lds, const Gemm g, const Sched& S, const Epi& E) {
;     ...
;         for (int t = 0; t < nt; t += 2) {
;     ...
;             PG8_WAIT_V(8); PG8_WAIT_L(0); PG8_BAR; PG8_MMA(0, 0, At, B0); PG8_MMA(0, 1, At, B1); PG8_BAR; PG8_SCHED;
;             PG8_LDA(At, 1, 1); PG8_STAGE(PG8_SB(1, 0), b3, voffB); PG8_STAGE(PG8_SB(1, 1), b3 + hstep, voffB); PG8_STAGE(PG8_SA(1, 0), a3, voffA);
;             PG8_WAIT_V(8); PG8_WAIT_L(0); PG8_BAR; PG8_MMA(1, 0, At, B0); PG8_MMA(1, 1, At, B1); PG8_BAR; PG8_SCHED;
;     ...
;         if constexpr (ALIGN_EPI) { if (wr == 0) PG8_BAR; }
	s_setprio 1
	s_waitcnt lgkmcnt(0)
	v_mfma_f32_16x16x32_bf16 v[124:127], v[142:145], v[184:187], v[124:127]
	v_mfma_f32_16x16x32_bf16 v[120:123], v[160:163], v[184:187], v[120:123]
	v_mfma_f32_16x16x32_bf16 v[108:111], v[142:145], v[198:201], v[108:111]
	v_mfma_f32_16x16x32_bf16 v[104:107], v[160:163], v[198:201], v[104:107]
	v_mfma_f32_16x16x32_bf16 v[92:95], v[142:145], v[206:209], v[92:95]
	v_mfma_f32_16x16x32_bf16 v[88:91], v[160:163], v[206:209], v[88:91]
	v_mfma_f32_16x16x32_bf16 v[76:79], v[142:145], v[214:217], v[76:79]
	v_mfma_f32_16x16x32_bf16 v[72:75], v[160:163], v[214:217], v[72:75]
	v_mfma_f32_16x16x32_bf16 v[124:127], v[156:159], v[188:191], v[124:127]
	v_mfma_f32_16x16x32_bf16 v[120:123], v[164:167], v[188:191], v[120:123]
	v_mfma_f32_16x16x32_bf16 v[108:111], v[156:159], v[202:205], v[108:111]
	v_mfma_f32_16x16x32_bf16 v[104:107], v[164:167], v[202:205], v[104:107]
	v_mfma_f32_16x16x32_bf16 v[92:95], v[156:159], v[210:213], v[92:95]
	v_mfma_f32_16x16x32_bf16 v[88:91], v[164:167], v[210:213], v[88:91]
	v_mfma_f32_16x16x32_bf16 v[76:79], v[156:159], v[228:231], v[76:79]
	v_mfma_f32_16x16x32_bf16 v[72:75], v[164:167], v[228:231], v[72:75]
	s_setprio 0
	s_setprio 1
	v_mfma_f32_16x16x32_bf16 v[116:119], v[168:171], v[184:187], v[116:119]
	v_mfma_f32_16x16x32_bf16 v[112:115], v[176:179], v[184:187], v[112:115]
	v_mfma_f32_16x16x32_bf16 v[100:103], v[168:171], v[198:201], v[100:103]
	v_mfma_f32_16x16x32_bf16 v[96:99], v[176:179], v[198:201], v[96:99]
	v_mfma_f32_16x16x32_bf16 v[84:87], v[168:171], v[206:209], v[84:87]
	v_mfma_f32_16x16x32_bf16 v[80:83], v[176:179], v[206:209], v[80:83]
	v_mfma_f32_16x16x32_bf16 v[68:71], v[168:171], v[214:217], v[68:71]
	v_mfma_f32_16x16x32_bf16 v[64:67], v[176:179], v[214:217], v[64:67]
	v_mfma_f32_16x16x32_bf16 v[116:119], v[172:175], v[188:191], v[116:119]
	v_mfma_f32_16x16x32_bf16 v[112:115], v[180:183], v[188:191], v[112:115]
	v_mfma_f32_16x16x32_bf16 v[100:103], v[172:175], v[202:205], v[100:103]
	v_mfma_f32_16x16x32_bf16 v[96:99], v[180:183], v[202:205], v[96:99]
	v_mfma_f32_16x16x32_bf16 v[84:87], v[172:175], v[210:213], v[84:87]
	v_mfma_f32_16x16x32_bf16 v[80:83], v[180:183], v[210:213], v[80:83]
	v_mfma_f32_16x16x32_bf16 v[68:71], v[172:175], v[228:231], v[68:71]
	v_mfma_f32_16x16x32_bf16 v[64:67], v[180:183], v[228:231], v[64:67]
	s_setprio 0
	s_barrier
	ds_read_b128 v[184:187], v155 offset:49152
	ds_read_b128 v[188:191], v155 offset:50176
	ds_read_b128 v[198:201], v155 offset:51200
	ds_read_b128 v[202:205], v155 offset:52224
	ds_read_b128 v[206:209], v155 offset:53248
	ds_read_b128 v[210:213], v155 offset:54272
	ds_read_b128 v[214:217], v155 offset:55296
	ds_read_b128 v[228:231], v155 offset:56320
	s_add_i32 s14, s91, s7
	s_mov_b32 m0, s14
	s_nop 0
	global_load_lds_dwordx4 v196, s[98:99]
	s_add_i32 m0, s14, 0x2000
	s_add_u32 s12, s12, 0x100080
	s_addc_u32 s13, s13, 0
	s_add_i32 s14, s58, s7
	global_load_lds_dwordx4 v132, s[98:99]
	s_mov_b32 m0, s14
	s_nop 0
	global_load_lds_dwordx4 v196, s[12:13]
	s_add_i32 m0, s14, 0x2000
	s_nop 0
	global_load_lds_dwordx4 v132, s[12:13]
	s_nop 0
	s_waitcnt vmcnt(6)
	s_waitcnt lgkmcnt(0)
	s_barrier
	s_setprio 1
	s_waitcnt lgkmcnt(0)
	v_mfma_f32_16x16x32_bf16 v[60:63], v[142:145], v[184:187], v[60:63]
	v_mfma_f32_16x16x32_bf16 v[56:59], v[160:163], v[184:187], v[56:59]
	v_mfma_f32_16x16x32_bf16 v[44:47], v[142:145], v[198:201], v[44:47]
	v_mfma_f32_16x16x32_bf16 v[40:43], v[160:163], v[198:201], v[40:43]
	v_mfma_f32_16x16x32_bf16 v[28:31], v[142:145], v[206:209], v[28:31]
	v_mfma_f32_16x16x32_bf16 v[24:27], v[160:163], v[206:209], v[24:27]
	v_mfma_f32_16x16x32_bf16 v[12:15], v[142:145], v[214:217], v[12:15]
	v_mfma_f32_16x16x32_bf16 v[8:11], v[160:163], v[214:217], v[8:11]
	v_mfma_f32_16x16x32_bf16 v[60:63], v[156:159], v[188:191], v[60:63]
	v_mfma_f32_16x16x32_bf16 v[56:59], v[164:167], v[188:191], v[56:59]
	v_mfma_f32_16x16x32_bf16 v[44:47], v[156:159], v[202:205], v[44:47]
	v_mfma_f32_16x16x32_bf16 v[40:43], v[164:167], v[202:205], v[40:43]
	v_mfma_f32_16x16x32_bf16 v[28:31], v[156:159], v[210:213], v[28:31]
	v_mfma_f32_16x16x32_bf16 v[24:27], v[164:167], v[210:213], v[24:27]
	v_mfma_f32_16x16x32_bf16 v[12:15], v[156:159], v[228:231], v[12:15]
	v_mfma_f32_16x16x32_bf16 v[8:11], v[164:167], v[228:231], v[8:11]
	s_setprio 0
	s_setprio 1
	v_mfma_f32_16x16x32_bf16 v[52:55], v[168:171], v[184:187], v[52:55]
	v_mfma_f32_16x16x32_bf16 v[48:51], v[176:179], v[184:187], v[48:51]
	v_mfma_f32_16x16x32_bf16 v[36:39], v[168:171], v[198:201], v[36:39]
	v_mfma_f32_16x16x32_bf16 v[32:35], v[176:179], v[198:201], v[32:35]
	v_mfma_f32_16x16x32_bf16 v[20:23], v[168:171], v[206:209], v[20:23]
	v_mfma_f32_16x16x32_bf16 v[16:19], v[176:179], v[206:209], v[16:19]
	v_mfma_f32_16x16x32_bf16 v[4:7], v[168:171], v[214:217], v[4:7]
	v_mfma_f32_16x16x32_bf16 v[0:3], v[176:179], v[214:217], v[0:3]
	v_mfma_f32_16x16x32_bf16 v[52:55], v[172:175], v[188:191], v[52:55]
	v_mfma_f32_16x16x32_bf16 v[48:51], v[180:183], v[188:191], v[48:51]
	v_mfma_f32_16x16x32_bf16 v[36:39], v[172:175], v[202:205], v[36:39]
	v_mfma_f32_16x16x32_bf16 v[32:35], v[180:183], v[202:205], v[32:35]
	v_mfma_f32_16x16x32_bf16 v[20:23], v[172:175], v[210:213], v[20:23]
	v_mfma_f32_16x16x32_bf16 v[16:19], v[180:183], v[210:213], v[16:19]
	v_mfma_f32_16x16x32_bf16 v[4:7], v[172:175], v[228:231], v[4:7]
	v_mfma_f32_16x16x32_bf16 v[0:3], v[180:183], v[228:231], v[0:3]
	s_setprio 0
	s_barrier
	s_add_i32 s42, s42, 2
	s_add_u32 s10, s10, 0x100
	s_addc_u32 s11, s11, 0
	s_add_u32 s25, s25, 0x100
	s_addc_u32 s41, s41, 0
	s_cmp_gt_u32 s42, 61
	s_cbranch_scc0 .LBB0_424
	s_nop 0
	s_and_b64 vcc, exec, s[20:21]
	s_cbranch_vccz .LBB0_427
	s_barrier

; #define PG8_STAGE(bufoff, gbase, voff) do { _Pragma("unroll") for (int _i = 0; _i < 2; ++_i) \
;         __builtin_amdgcn_global_load_lds((const unsigned*)((const char*)(gbase) + (voff)[_i]), (LAS unsigned*)(lds + (bufoff) + ldsw + _i * 8192), 16, 0, 0); } while (0)
; #define PG8_LDA(dst, b, h) do { _Pragma("unroll") for (int m = 0; m < 4; ++m) _Pragma("unroll") for (int k = 0; k < 2; ++k) dst[m][k] = *(const LAS bf16x8*)(lds + PG8_SA(b, h) + aoff + m * 2048 + k * 1024); } while (0)
; #define PG8_LDB(dst, b, h) do { _Pragma("unroll") for (int n = 0; n < 2; ++n) _Pragma("unroll") for (int k = 0; k < 2; ++k) dst[n][k] = *(const LAS bf16x8*)(lds + PG8_SB(b, h) + boff + n * 2048 + k * 1024); } while (0)
; #define PG8_MMA(ai, bj, At, Bt) do { __builtin_amdgcn_s_setprio(1); _Pragma("unroll") for (int m = 0; m < 4; ++m) _Pragma("unroll") for (int n = 0; n < 2; ++n) _Pragma("unroll") for (int k = 0; k < 2; ++k) \
;         acc[ai][bj][m][n] = __builtin_amdgcn_mfma_f32_16x16x32_bf16(Bt[n][k], At[m][k], acc[ai][bj][m][n], 0, 0, 0); __builtin_amdgcn_s_setprio(0); } while (0)
; #define PG8_WAIT_V(n) asm volatile("s_waitcnt vmcnt(" #n ")" ::: "memory")
; #define PG8_WAIT_L(n) asm volatile("s_waitcnt lgkmcnt(" #n ")" ::: "memory")
; #define PG8_BAR __builtin_amdgcn_s_barrier()
; template <class Epi, class Sched, bool ALIGN_EPI = false, bool SP2 = false>
; __device__ __forceinline__ void gemm_phase(LAS unsigned char* lds, const Gemm g, const Sched& S, const Epi& E) {
;     ...
;             const bool last = (t == nt - 2);
;             const char* a1 = cA + (size_t)(t + 1) * kstep;
;             const char* a2 = last ? nA : cA + (size_t)(t + 2) * kstep; const char* b2 = last ? nB : cB + (size_t)(t + 2) * kstep;
;             const char* a3 = a2 + kstep; const char* b3 = b2 + kstep;
;             if (last && has_next) S.a_ready(nxt);
;             if constexpr (SP2) {
;             PG8_LDB(B0, 0, 0); PG8_LDB(B1, 0, 1); PG8_SCHED; PG8_LDA(At, 0, 0); PG8_STAGE(PG8_SA(1, 1), a1 + hstep, voffA);
;             PG8_WAIT_V(8); PG8_WAIT_L(0); PG8_BAR; PG8_MMA(0, 0, At, B0); PG8_MMA(0, 1, At, B1); PG8_BAR; PG8_SCHED;
;             PG8_LDA(At, 0, 1); PG8_STAGE(PG8_SB(0, 0), b2, voffB); PG8_STAGE(PG8_SB(0, 1), b2 + hstep, voffB); PG8_STAGE(PG8_SA(0, 0), a2, voffA);
;             PG8_WAIT_V(8); PG8_WAIT_L(0); PG8_BAR; PG8_MMA(1, 0, At, B0); PG8_MMA(1, 1, At, B1); PG8_BAR; PG8_SCHED;
.LBB0_510:
	v_add_u32_e32 v138, s48, v141
	ds_read_b128 v[144:147], v138
	ds_read_b128 v[148:151], v138 offset:1024
	ds_read_b128 v[152:155], v138 offset:2048
	ds_read_b128 v[156:159], v138 offset:3072
	v_add_u32_e32 v138, s90, v141
	ds_read_b128 v[160:163], v138
	ds_read_b128 v[164:167], v138 offset:1024
	ds_read_b128 v[168:171], v138 offset:2048
	ds_read_b128 v[172:175], v138 offset:3072
	ds_read_b128 v[176:179], v143
	ds_read_b128 v[180:183], v143 offset:1024
	ds_read_b128 v[184:187], v143 offset:2048
	ds_read_b128 v[188:191], v143 offset:3072
	ds_read_b128 v[198:201], v143 offset:4096
	ds_read_b128 v[202:205], v143 offset:5120
	ds_read_b128 v[206:209], v143 offset:6144
	ds_read_b128 v[210:213], v143 offset:7168
	s_add_u32 s100, s24, 0xfff00000
	s_addc_u32 s101, s25, -1
	s_add_u32 s26, s24, 0xfff00080
	s_addc_u32 s27, s25, -1
	s_cmp_eq_u32 s41, 60
	s_cselect_b32 s29, s19, s27
	s_cselect_b32 s28, s37, s26
	s_cselect_b32 s27, s15, s40
	s_cselect_b32 s26, s38, s39
	s_add_i32 m0, s3, 0xc000
	s_mov_b32 m0, s30
	s_nop 0
	global_load_lds_dwordx4 v132, s[100:101]
	s_mov_b32 m0, s31
	s_nop 0
	global_load_lds_dwordx4 v130, s[100:101]
	s_add_i32 m0, s3, 0xc000
	s_nop 0
	global_load_lds_dwordx4 v134, s[24:25]
	s_add_i32 m0, s3, 0xe000
	s_nop 0
	global_load_lds_dwordx4 v136, s[24:25]
	s_waitcnt vmcnt(8)
	s_waitcnt lgkmcnt(0)
	s_barrier
	s_setprio 1
	s_waitcnt lgkmcnt(0)
	v_mfma_f32_16x16x32_bf16 v[124:127], v[144:147], v[176:179], v[124:127]
	v_mfma_f32_16x16x32_bf16 v[120:123], v[152:155], v[176:179], v[120:123]
	v_mfma_f32_16x16x32_bf16 v[116:119], v[144:147], v[184:187], v[116:119]
	v_mfma_f32_16x16x32_bf16 v[108:111], v[152:155], v[184:187], v[108:111]
	v_mfma_f32_16x16x32_bf16 v[100:103], v[144:147], v[198:201], v[100:103]
	v_mfma_f32_16x16x32_bf16 v[92:95], v[152:155], v[198:201], v[92:95]
	v_mfma_f32_16x16x32_bf16 v[80:83], v[144:147], v[206:209], v[80:83]
	v_mfma_f32_16x16x32_bf16 v[72:75], v[152:155], v[206:209], v[72:75]
	v_mfma_f32_16x16x32_bf16 v[124:127], v[148:151], v[180:183], v[124:127]
	v_mfma_f32_16x16x32_bf16 v[120:123], v[156:159], v[180:183], v[120:123]
	v_mfma_f32_16x16x32_bf16 v[116:119], v[148:151], v[188:191], v[116:119]
	v_mfma_f32_16x16x32_bf16 v[108:111], v[156:159], v[188:191], v[108:111]
	v_mfma_f32_16x16x32_bf16 v[100:103], v[148:151], v[202:205], v[100:103]
	v_mfma_f32_16x16x32_bf16 v[92:95], v[156:159], v[202:205], v[92:95]
	v_mfma_f32_16x16x32_bf16 v[80:83], v[148:151], v[210:213], v[80:83]
	v_mfma_f32_16x16x32_bf16 v[72:75], v[156:159], v[210:213], v[72:75]
	s_setprio 0
	s_setprio 1
	v_mfma_f32_16x16x32_bf16 v[112:115], v[160:163], v[176:179], v[112:115]
	v_mfma_f32_16x16x32_bf16 v[104:107], v[168:171], v[176:179], v[104:107]
	v_mfma_f32_16x16x32_bf16 v[96:99], v[160:163], v[184:187], v[96:99]
	v_mfma_f32_16x16x32_bf16 v[88:91], v[168:171], v[184:187], v[88:91]
	v_mfma_f32_16x16x32_bf16 v[84:87], v[160:163], v[198:201], v[84:87]
	v_mfma_f32_16x16x32_bf16 v[76:79], v[168:171], v[198:201], v[76:79]
	v_mfma_f32_16x16x32_bf16 v[68:71], v[160:163], v[206:209], v[68:71]
	v_mfma_f32_16x16x32_bf16 v[64:67], v[168:171], v[206:209], v[64:67]
	v_mfma_f32_16x16x32_bf16 v[112:115], v[164:167], v[180:183], v[112:115]
	v_mfma_f32_16x16x32_bf16 v[104:107], v[172:175], v[180:183], v[104:107]
	v_mfma_f32_16x16x32_bf16 v[96:99], v[164:167], v[188:191], v[96:99]
	v_mfma_f32_16x16x32_bf16 v[88:91], v[172:175], v[188:191], v[88:91]
	v_mfma_f32_16x16x32_bf16 v[84:87], v[164:167], v[202:205], v[84:87]
	v_mfma_f32_16x16x32_bf16 v[76:79], v[172:175], v[202:205], v[76:79]
	v_mfma_f32_16x16x32_bf16 v[68:71], v[164:167], v[210:213], v[68:71]
	v_mfma_f32_16x16x32_bf16 v[64:67], v[172:175], v[210:213], v[64:67]
	s_setprio 0
	s_barrier
	ds_read_b128 v[176:179], v143 offset:16384
	ds_read_b128 v[180:183], v143 offset:17408
	ds_read_b128 v[184:187], v143 offset:18432
	ds_read_b128 v[188:191], v143 offset:19456
	ds_read_b128 v[198:201], v143 offset:20480
	ds_read_b128 v[202:205], v143 offset:21504
	ds_read_b128 v[206:209], v143 offset:22528
	ds_read_b128 v[210:213], v143 offset:23552
	s_add_u32 s98, s26, 0x80
	s_addc_u32 s99, s27, 0
	s_add_i32 s42, s48, s2
	s_mov_b32 m0, s42
	s_nop 0
	global_load_lds_dwordx4 v196, s[26:27]
	s_add_i32 m0, s42, 0x2000
	s_add_u32 s46, s26, 0x100000
	s_addc_u32 s47, s27, 0
	s_add_i32 s42, s90, s2
	global_load_lds_dwordx4 v128, s[26:27]
	s_mov_b32 m0, s42
	s_nop 0
	global_load_lds_dwordx4 v196, s[46:47]
	s_add_i32 m0, s42, 0x2000
	s_nop 0
	global_load_lds_dwordx4 v128, s[46:47]
	s_waitcnt vmcnt(6)
	s_waitcnt lgkmcnt(0)
	s_barrier
; #define PG8_STAGE(bufoff, gbase, voff) do { _Pragma("unroll") for (int _i = 0; _i < 2; ++_i) \
;         __builtin_amdgcn_global_load_lds((const unsigned*)((const char*)(gbase) + (voff)[_i]), (LAS unsigned*)(lds + (bufoff) + ldsw + _i * 8192), 16, 0, 0); } while (0)
; #define PG8_LDA(dst, b, h) do { _Pragma("unroll") for (int m = 0; m < 4; ++m) _Pragma("unroll") for (int k = 0; k < 2; ++k) dst[m][k] = *(const LAS bf16x8*)(lds + PG8_SA(b, h) + aoff + m * 2048 + k * 1024); } while (0)
; #define PG8_LDB(dst, b, h) do { _Pragma("unroll") for (int n = 0; n < 2; ++n) _Pragma("unroll") for (int k = 0; k < 2; ++k) dst[n][k] = *(const LAS bf16x8*)(lds + PG8_SB(b, h) + boff + n * 2048 + k * 1024); } while (0)
; #define PG8_MMA(ai, bj, At, Bt) do { __builtin_amdgcn_s_setprio(1); _Pragma("unroll") for (int m = 0; m < 4; ++m) _Pragma("unroll") for (int n = 0; n < 2; ++n) _Pragma("unroll") for (int k = 0; k < 2; ++k) \
;         acc[ai][bj][m][n] = __builtin_amdgcn_mfma_f32_16x16x32_bf16(Bt[n][k], At[m][k], acc[ai][bj][m][n], 0, 0, 0); __builtin_amdgcn_s_setprio(0); } while (0)
; #define PG8_WAIT_V(n) asm volatile("s_waitcnt vmcnt(" #n ")" ::: "memory")
; #define PG8_WAIT_L(n) asm volatile("s_waitcnt lgkmcnt(" #n ")" ::: "memory")
; #define PG8_BAR __builtin_amdgcn_s_barrier()
; #define PG8_SCHED __builtin_amdgcn_sched_barrier(0)
; template <class Epi, class Sched, bool ALIGN_EPI = false, bool SP2 = false>
; __device__ __forceinline__ void gemm_phase(LAS unsigned char* lds, const Gemm g, const Sched& S, const Epi& E) {
;     ...
;             PG8_WAIT_V(8); PG8_WAIT_L(0); PG8_BAR; PG8_MMA(1, 0, At, B0); PG8_MMA(1, 1, At, B1); PG8_BAR; PG8_SCHED;
;             PG8_LDB(B0, 1, 0); PG8_LDB(B1, 1, 1); PG8_SCHED; PG8_LDA(At, 1, 0); PG8_STAGE(PG8_SA(0, 1), a2 + hstep, voffA);
;             PG8_WAIT_V(8); PG8_WAIT_L(0); PG8_BAR; PG8_MMA(0, 0, At, B0); PG8_MMA(0, 1, At, B1); PG8_BAR; PG8_SCHED;
	s_setprio 1
	s_waitcnt lgkmcnt(0)
	v_mfma_f32_16x16x32_bf16 v[60:63], v[144:147], v[176:179], v[60:63]
	v_mfma_f32_16x16x32_bf16 v[56:59], v[152:155], v[176:179], v[56:59]
	v_mfma_f32_16x16x32_bf16 v[52:55], v[144:147], v[184:187], v[52:55]
	v_mfma_f32_16x16x32_bf16 v[44:47], v[152:155], v[184:187], v[44:47]
	v_mfma_f32_16x16x32_bf16 v[36:39], v[144:147], v[198:201], v[36:39]
	v_mfma_f32_16x16x32_bf16 v[28:31], v[152:155], v[198:201], v[28:31]
	v_mfma_f32_16x16x32_bf16 v[20:23], v[144:147], v[206:209], v[20:23]
	v_mfma_f32_16x16x32_bf16 v[12:15], v[152:155], v[206:209], v[12:15]
	v_mfma_f32_16x16x32_bf16 v[60:63], v[148:151], v[180:183], v[60:63]
	v_mfma_f32_16x16x32_bf16 v[56:59], v[156:159], v[180:183], v[56:59]
	v_mfma_f32_16x16x32_bf16 v[52:55], v[148:151], v[188:191], v[52:55]
	v_mfma_f32_16x16x32_bf16 v[44:47], v[156:159], v[188:191], v[44:47]
	v_mfma_f32_16x16x32_bf16 v[36:39], v[148:151], v[202:205], v[36:39]
	v_mfma_f32_16x16x32_bf16 v[28:31], v[156:159], v[202:205], v[28:31]
	v_mfma_f32_16x16x32_bf16 v[20:23], v[148:151], v[210:213], v[20:23]
	v_mfma_f32_16x16x32_bf16 v[12:15], v[156:159], v[210:213], v[12:15]
	s_setprio 0
	s_setprio 1
	v_mfma_f32_16x16x32_bf16 v[48:51], v[160:163], v[176:179], v[48:51]
	v_mfma_f32_16x16x32_bf16 v[40:43], v[168:171], v[176:179], v[40:43]
	v_mfma_f32_16x16x32_bf16 v[32:35], v[160:163], v[184:187], v[32:35]
	v_mfma_f32_16x16x32_bf16 v[24:27], v[168:171], v[184:187], v[24:27]
	v_mfma_f32_16x16x32_bf16 v[16:19], v[160:163], v[198:201], v[16:19]
	v_mfma_f32_16x16x32_bf16 v[8:11], v[168:171], v[198:201], v[8:11]
	v_mfma_f32_16x16x32_bf16 v[4:7], v[160:163], v[206:209], v[4:7]
	v_mfma_f32_16x16x32_bf16 v[0:3], v[168:171], v[206:209], v[0:3]
	v_mfma_f32_16x16x32_bf16 v[48:51], v[164:167], v[180:183], v[48:51]
	v_mfma_f32_16x16x32_bf16 v[40:43], v[172:175], v[180:183], v[40:43]
	v_mfma_f32_16x16x32_bf16 v[32:35], v[164:167], v[188:191], v[32:35]
	v_mfma_f32_16x16x32_bf16 v[24:27], v[172:175], v[188:191], v[24:27]
	v_mfma_f32_16x16x32_bf16 v[16:19], v[164:167], v[202:205], v[16:19]
	v_mfma_f32_16x16x32_bf16 v[8:11], v[172:175], v[202:205], v[8:11]
	v_mfma_f32_16x16x32_bf16 v[4:7], v[164:167], v[210:213], v[4:7]
	v_mfma_f32_16x16x32_bf16 v[0:3], v[172:175], v[210:213], v[0:3]
	s_setprio 0
	s_barrier
	v_add_u32_e32 v156, s91, v141
	v_add_u32_e32 v172, s58, v141
	ds_read_b128 v[144:147], v156
	ds_read_b128 v[148:151], v156 offset:1024
	ds_read_b128 v[152:155], v156 offset:2048
	ds_read_b128 v[156:159], v156 offset:3072
	ds_read_b128 v[160:163], v172
	ds_read_b128 v[164:167], v172 offset:1024
	ds_read_b128 v[168:171], v172 offset:2048
	ds_read_b128 v[172:175], v172 offset:3072
	ds_read_b128 v[176:179], v143 offset:32768
	ds_read_b128 v[180:183], v143 offset:33792
	ds_read_b128 v[184:187], v143 offset:34816
	ds_read_b128 v[188:191], v143 offset:35840
	ds_read_b128 v[198:201], v143 offset:36864
	ds_read_b128 v[202:205], v143 offset:37888
	ds_read_b128 v[206:209], v143 offset:38912
	ds_read_b128 v[210:213], v143 offset:39936
	s_mov_b32 m0, s3
	s_nop 0
	global_load_lds_dwordx4 v132, s[28:29]
	s_mov_b32 m0, s6
	s_nop 0
	global_load_lds_dwordx4 v130, s[28:29]
	s_add_u32 s28, s28, 0x100000
	s_addc_u32 s29, s29, 0
	s_mov_b32 m0, s7
	s_nop 0
	global_load_lds_dwordx4 v132, s[28:29]
	s_mov_b32 m0, s17
	s_nop 0
	global_load_lds_dwordx4 v130, s[28:29]
	s_waitcnt vmcnt(8)
	s_waitcnt lgkmcnt(0)
	s_barrier
; #define PG8_STAGE(bufoff, gbase, voff) do { _Pragma("unroll") for (int _i = 0; _i < 2; ++_i) \
;         __builtin_amdgcn_global_load_lds((const unsigned*)((const char*)(gbase) + (voff)[_i]), (LAS unsigned*)(lds + (bufoff) + ldsw + _i * 8192), 16, 0, 0); } while (0)
; #define PG8_LDA(dst, b, h) do { _Pragma("unroll") for (int m = 0; m < 4; ++m) _Pragma("unroll") for (int k = 0; k < 2; ++k) dst[m][k] = *(const LAS bf16x8*)(lds + PG8_SA(b, h) + aoff + m * 2048 + k * 1024); } while (0)
; #define PG8_MMA(ai, bj, At, Bt) do { __builtin_amdgcn_s_setprio(1); _Pragma("unroll") for (int m = 0; m < 4; ++m) _Pragma("unroll") for (int n = 0; n < 2; ++n) _Pragma("unroll") for (int k = 0; k < 2; ++k) \
;         acc[ai][bj][m][n] = __builtin_amdgcn_mfma_f32_16x16x32_bf16(Bt[n][k], At[m][k], acc[ai][bj][m][n], 0, 0, 0); __builtin_amdgcn_s_setprio(0); } while (0)
; #define PG8_WAIT_V(n) asm volatile("s_waitcnt vmcnt(" #n ")" ::: "memory")
; #define PG8_WAIT_L(n) asm volatile("s_waitcnt lgkmcnt(" #n ")" ::: "memory")
; #define PG8_BAR __builtin_amdgcn_s_barrier()
; #define PG8_SCHED __builtin_amdgcn_sched_barrier(0)
; template <class Epi, class Sched, bool ALIGN_EPI = false, bool SP2 = false>
; __device__ __forceinline__ void gemm_phase(LAS unsigned char* lds, const Gemm g, const Sched& S, const Epi& E) {
;     ...
;         for (int t = 0; t < nt; t += 2) {
;     ...
;             PG8_WAIT_V(8); PG8_WAIT_L(0); PG8_BAR; PG8_MMA(0, 0, At, B0); PG8_MMA(0, 1, At, B1); PG8_BAR; PG8_SCHED;
;             PG8_LDA(At, 1, 1); PG8_STAGE(PG8_SB(1, 0), b3, voffB); PG8_STAGE(PG8_SB(1, 1), b3 + hstep, voffB); PG8_STAGE(PG8_SA(1, 0), a3, voffA);
;             PG8_WAIT_V(8); PG8_WAIT_L(0); PG8_BAR; PG8_MMA(1, 0, At, B0); PG8_MMA(1, 1, At, B1); PG8_BAR; PG8_SCHED;
;     ...
;         if constexpr (ALIGN_EPI) { if (wr == 0) PG8_BAR; }
	s_setprio 1
	s_waitcnt lgkmcnt(0)
	v_mfma_f32_16x16x32_bf16 v[124:127], v[144:147], v[176:179], v[124:127]
	v_mfma_f32_16x16x32_bf16 v[120:123], v[152:155], v[176:179], v[120:123]
	v_mfma_f32_16x16x32_bf16 v[116:119], v[144:147], v[184:187], v[116:119]
	v_mfma_f32_16x16x32_bf16 v[108:111], v[152:155], v[184:187], v[108:111]
	v_mfma_f32_16x16x32_bf16 v[100:103], v[144:147], v[198:201], v[100:103]
	v_mfma_f32_16x16x32_bf16 v[92:95], v[152:155], v[198:201], v[92:95]
	v_mfma_f32_16x16x32_bf16 v[80:83], v[144:147], v[206:209], v[80:83]
	v_mfma_f32_16x16x32_bf16 v[72:75], v[152:155], v[206:209], v[72:75]
	v_mfma_f32_16x16x32_bf16 v[124:127], v[148:151], v[180:183], v[124:127]
	v_mfma_f32_16x16x32_bf16 v[120:123], v[156:159], v[180:183], v[120:123]
	v_mfma_f32_16x16x32_bf16 v[116:119], v[148:151], v[188:191], v[116:119]
	v_mfma_f32_16x16x32_bf16 v[108:111], v[156:159], v[188:191], v[108:111]
	v_mfma_f32_16x16x32_bf16 v[100:103], v[148:151], v[202:205], v[100:103]
	v_mfma_f32_16x16x32_bf16 v[92:95], v[156:159], v[202:205], v[92:95]
	v_mfma_f32_16x16x32_bf16 v[80:83], v[148:151], v[210:213], v[80:83]
	v_mfma_f32_16x16x32_bf16 v[72:75], v[156:159], v[210:213], v[72:75]
	s_setprio 0
	s_setprio 1
	v_mfma_f32_16x16x32_bf16 v[112:115], v[160:163], v[176:179], v[112:115]
	v_mfma_f32_16x16x32_bf16 v[104:107], v[168:171], v[176:179], v[104:107]
	v_mfma_f32_16x16x32_bf16 v[96:99], v[160:163], v[184:187], v[96:99]
	v_mfma_f32_16x16x32_bf16 v[88:91], v[168:171], v[184:187], v[88:91]
	v_mfma_f32_16x16x32_bf16 v[84:87], v[160:163], v[198:201], v[84:87]
	v_mfma_f32_16x16x32_bf16 v[76:79], v[168:171], v[198:201], v[76:79]
	v_mfma_f32_16x16x32_bf16 v[68:71], v[160:163], v[206:209], v[68:71]
	v_mfma_f32_16x16x32_bf16 v[64:67], v[168:171], v[206:209], v[64:67]
	v_mfma_f32_16x16x32_bf16 v[112:115], v[164:167], v[180:183], v[112:115]
	v_mfma_f32_16x16x32_bf16 v[104:107], v[172:175], v[180:183], v[104:107]
	v_mfma_f32_16x16x32_bf16 v[96:99], v[164:167], v[188:191], v[96:99]
	v_mfma_f32_16x16x32_bf16 v[88:91], v[172:175], v[188:191], v[88:91]
	v_mfma_f32_16x16x32_bf16 v[84:87], v[164:167], v[202:205], v[84:87]
	v_mfma_f32_16x16x32_bf16 v[76:79], v[172:175], v[202:205], v[76:79]
	v_mfma_f32_16x16x32_bf16 v[68:71], v[164:167], v[210:213], v[68:71]
	v_mfma_f32_16x16x32_bf16 v[64:67], v[172:175], v[210:213], v[64:67]
	s_setprio 0
	s_barrier
	ds_read_b128 v[176:179], v143 offset:49152
	ds_read_b128 v[180:183], v143 offset:50176
	ds_read_b128 v[184:187], v143 offset:51200
	ds_read_b128 v[188:191], v143 offset:52224
	ds_read_b128 v[198:201], v143 offset:53248
	ds_read_b128 v[202:205], v143 offset:54272
	ds_read_b128 v[206:209], v143 offset:55296
	ds_read_b128 v[210:213], v143 offset:56320
	s_add_i32 s28, s91, s2
	s_mov_b32 m0, s28
	s_nop 0
	global_load_lds_dwordx4 v196, s[98:99]
	s_add_i32 m0, s28, 0x2000
	s_add_u32 s26, s26, 0x100080
	s_addc_u32 s27, s27, 0
	s_add_i32 s28, s58, s2
	global_load_lds_dwordx4 v128, s[98:99]
	s_mov_b32 m0, s28
	s_nop 0
	global_load_lds_dwordx4 v196, s[26:27]
	s_add_i32 m0, s28, 0x2000
	s_nop 0
	global_load_lds_dwordx4 v128, s[26:27]
	s_nop 0
	s_waitcnt vmcnt(6)
	s_waitcnt lgkmcnt(0)
	s_barrier
	s_setprio 1
	s_waitcnt lgkmcnt(0)
	v_mfma_f32_16x16x32_bf16 v[60:63], v[144:147], v[176:179], v[60:63]
	v_mfma_f32_16x16x32_bf16 v[56:59], v[152:155], v[176:179], v[56:59]
	v_mfma_f32_16x16x32_bf16 v[52:55], v[144:147], v[184:187], v[52:55]
	v_mfma_f32_16x16x32_bf16 v[44:47], v[152:155], v[184:187], v[44:47]
	v_mfma_f32_16x16x32_bf16 v[36:39], v[144:147], v[198:201], v[36:39]
	v_mfma_f32_16x16x32_bf16 v[28:31], v[152:155], v[198:201], v[28:31]
	v_mfma_f32_16x16x32_bf16 v[20:23], v[144:147], v[206:209], v[20:23]
	v_mfma_f32_16x16x32_bf16 v[12:15], v[152:155], v[206:209], v[12:15]
	v_mfma_f32_16x16x32_bf16 v[60:63], v[148:151], v[180:183], v[60:63]
	v_mfma_f32_16x16x32_bf16 v[56:59], v[156:159], v[180:183], v[56:59]
	v_mfma_f32_16x16x32_bf16 v[52:55], v[148:151], v[188:191], v[52:55]
	v_mfma_f32_16x16x32_bf16 v[44:47], v[156:159], v[188:191], v[44:47]
	v_mfma_f32_16x16x32_bf16 v[36:39], v[148:151], v[202:205], v[36:39]
	v_mfma_f32_16x16x32_bf16 v[28:31], v[156:159], v[202:205], v[28:31]
	v_mfma_f32_16x16x32_bf16 v[20:23], v[148:151], v[210:213], v[20:23]
	v_mfma_f32_16x16x32_bf16 v[12:15], v[156:159], v[210:213], v[12:15]
	s_setprio 0
	s_setprio 1
	v_mfma_f32_16x16x32_bf16 v[48:51], v[160:163], v[176:179], v[48:51]
	v_mfma_f32_16x16x32_bf16 v[40:43], v[168:171], v[176:179], v[40:43]
	v_mfma_f32_16x16x32_bf16 v[32:35], v[160:163], v[184:187], v[32:35]
	v_mfma_f32_16x16x32_bf16 v[24:27], v[168:171], v[184:187], v[24:27]
	v_mfma_f32_16x16x32_bf16 v[16:19], v[160:163], v[198:201], v[16:19]
	v_mfma_f32_16x16x32_bf16 v[8:11], v[168:171], v[198:201], v[8:11]
	v_mfma_f32_16x16x32_bf16 v[4:7], v[160:163], v[206:209], v[4:7]
	v_mfma_f32_16x16x32_bf16 v[0:3], v[168:171], v[206:209], v[0:3]
	v_mfma_f32_16x16x32_bf16 v[48:51], v[164:167], v[180:183], v[48:51]
	v_mfma_f32_16x16x32_bf16 v[40:43], v[172:175], v[180:183], v[40:43]
	v_mfma_f32_16x16x32_bf16 v[32:35], v[164:167], v[188:191], v[32:35]
	v_mfma_f32_16x16x32_bf16 v[24:27], v[172:175], v[188:191], v[24:27]
	v_mfma_f32_16x16x32_bf16 v[16:19], v[164:167], v[202:205], v[16:19]
	v_mfma_f32_16x16x32_bf16 v[8:11], v[172:175], v[202:205], v[8:11]
	v_mfma_f32_16x16x32_bf16 v[4:7], v[164:167], v[210:213], v[4:7]
	v_mfma_f32_16x16x32_bf16 v[0:3], v[172:175], v[210:213], v[0:3]
	s_setprio 0
	s_barrier
	s_add_i32 s41, s41, 2
	s_add_u32 s24, s24, 0x100
	s_addc_u32 s25, s25, 0
	s_add_u32 s39, s39, 0x100
	s_addc_u32 s40, s40, 0
	s_cmp_gt_u32 s41, 61
	s_cbranch_scc0 .LBB0_510
	s_nop 0
	s_and_b64 vcc, exec, s[10:11]
	s_cbranch_vccz .LBB0_513
	s_barrier

; #define PG8_STAGE(bufoff, gbase, voff) do { _Pragma("unroll") for (int _i = 0; _i < 2; ++_i) \
;         __builtin_amdgcn_global_load_lds((const unsigned*)((const char*)(gbase) + (voff)[_i]), (LAS unsigned*)(lds + (bufoff) + ldsw + _i * 8192), 16, 0, 0); } while (0)
; #define PG8_LDA(dst, b, h) do { _Pragma("unroll") for (int m = 0; m < 4; ++m) _Pragma("unroll") for (int k = 0; k < 2; ++k) dst[m][k] = *(const LAS bf16x8*)(lds + PG8_SA(b, h) + aoff + m * 2048 + k * 1024); } while (0)
; #define PG8_LDB(dst, b, h) do { _Pragma("unroll") for (int n = 0; n < 2; ++n) _Pragma("unroll") for (int k = 0; k < 2; ++k) dst[n][k] = *(const LAS bf16x8*)(lds + PG8_SB(b, h) + boff + n * 2048 + k * 1024); } while (0)
; #define PG8_MMA(ai, bj, At, Bt) do { __builtin_amdgcn_s_setprio(1); _Pragma("unroll") for (int m = 0; m < 4; ++m) _Pragma("unroll") for (int n = 0; n < 2; ++n) _Pragma("unroll") for (int k = 0; k < 2; ++k) \
;         acc[ai][bj][m][n] = __builtin_amdgcn_mfma_f32_16x16x32_bf16(Bt[n][k], At[m][k], acc[ai][bj][m][n], 0, 0, 0); __builtin_amdgcn_s_setprio(0); } while (0)
; #define PG8_WAIT_V(n) asm volatile("s_waitcnt vmcnt(" #n ")" ::: "memory")
; #define PG8_WAIT_L(n) asm volatile("s_waitcnt lgkmcnt(" #n ")" ::: "memory")
; #define PG8_BAR __builtin_amdgcn_s_barrier()
; template <class Epi, class Sched, bool ALIGN_EPI = false, bool SP2 = false>
; __device__ __forceinline__ void gemm_phase(LAS unsigned char* lds, const Gemm g, const Sched& S, const Epi& E) {
;     ...
;             const bool last = (t == nt - 2);
;             const char* a1 = cA + (size_t)(t + 1) * kstep;
;             const char* a2 = last ? nA : cA + (size_t)(t + 2) * kstep; const char* b2 = last ? nB : cB + (size_t)(t + 2) * kstep;
;             const char* a3 = a2 + kstep; const char* b3 = b2 + kstep;
;             if (last && has_next) S.a_ready(nxt);
;             if constexpr (SP2) {
;             PG8_LDB(B0, 0, 0); PG8_LDB(B1, 0, 1); PG8_SCHED; PG8_LDA(At, 0, 0); PG8_STAGE(PG8_SA(1, 1), a1 + hstep, voffA);
;             PG8_WAIT_V(8); PG8_WAIT_L(0); PG8_BAR; PG8_MMA(0, 0, At, B0); PG8_MMA(0, 1, At, B1); PG8_BAR; PG8_SCHED;
;             PG8_LDA(At, 0, 1); PG8_STAGE(PG8_SB(0, 0), b2, voffB); PG8_STAGE(PG8_SB(0, 1), b2 + hstep, voffB); PG8_STAGE(PG8_SA(0, 0), a2, voffA);
;             PG8_WAIT_V(8); PG8_WAIT_L(0); PG8_BAR; PG8_MMA(1, 0, At, B0); PG8_MMA(1, 1, At, B1); PG8_BAR; PG8_SCHED;
.LBB0_832:
	v_add_u32_e32 v150, s48, v157
	v_add_u32_e32 v154, s90, v157
	ds_read_b128 v[128:131], v150
	ds_read_b128 v[132:135], v150 offset:1024
	ds_read_b128 v[146:149], v150 offset:2048
	ds_read_b128 v[150:153], v150 offset:3072
	ds_read_b128 v[160:163], v154
	ds_read_b128 v[164:167], v154 offset:1024
	ds_read_b128 v[168:171], v154 offset:2048
	ds_read_b128 v[172:175], v154 offset:3072
	ds_read_b128 v[176:179], v159
	ds_read_b128 v[180:183], v159 offset:1024
	ds_read_b128 v[184:187], v159 offset:2048
	ds_read_b128 v[188:191], v159 offset:3072
	ds_read_b128 v[198:201], v159 offset:4096
	ds_read_b128 v[202:205], v159 offset:5120
	ds_read_b128 v[206:209], v159 offset:6144
	ds_read_b128 v[210:213], v159 offset:7168
	s_add_u32 s100, s10, 0xfff00000
	s_addc_u32 s101, s11, -1
	s_add_u32 s34, s10, 0xfff00080
	s_addc_u32 s35, s11, -1
	s_cmp_eq_u32 s62, 60
	s_cselect_b32 s37, s27, s35
	s_cselect_b32 s36, s47, s34
	s_cselect_b32 s35, s25, s59
	s_cselect_b32 s34, s49, s54
	s_add_i32 m0, s3, 0xc000
	s_mov_b32 m0, s41
	s_nop 0
	global_load_lds_dwordx4 v140, s[100:101]
	s_mov_b32 m0, s42
	s_nop 0
	global_load_lds_dwordx4 v138, s[100:101]
	s_add_i32 m0, s3, 0xc000
	s_nop 0
	global_load_lds_dwordx4 v142, s[10:11]
	s_add_i32 m0, s3, 0xe000
	s_nop 0
	global_load_lds_dwordx4 v144, s[10:11]
	s_waitcnt vmcnt(8)
	s_waitcnt lgkmcnt(0)
	s_barrier
	s_setprio 1
	s_waitcnt lgkmcnt(0)
	v_mfma_f32_16x16x32_bf16 v[124:127], v[128:131], v[176:179], v[124:127]
	v_mfma_f32_16x16x32_bf16 v[120:123], v[146:149], v[176:179], v[120:123]
	v_mfma_f32_16x16x32_bf16 v[108:111], v[128:131], v[184:187], v[108:111]
	v_mfma_f32_16x16x32_bf16 v[104:107], v[146:149], v[184:187], v[104:107]
	v_mfma_f32_16x16x32_bf16 v[92:95], v[128:131], v[198:201], v[92:95]
	v_mfma_f32_16x16x32_bf16 v[88:91], v[146:149], v[198:201], v[88:91]
	v_mfma_f32_16x16x32_bf16 v[76:79], v[128:131], v[206:209], v[76:79]
	v_mfma_f32_16x16x32_bf16 v[72:75], v[146:149], v[206:209], v[72:75]
	v_mfma_f32_16x16x32_bf16 v[124:127], v[132:135], v[180:183], v[124:127]
	v_mfma_f32_16x16x32_bf16 v[120:123], v[150:153], v[180:183], v[120:123]
	v_mfma_f32_16x16x32_bf16 v[108:111], v[132:135], v[188:191], v[108:111]
	v_mfma_f32_16x16x32_bf16 v[104:107], v[150:153], v[188:191], v[104:107]
	v_mfma_f32_16x16x32_bf16 v[92:95], v[132:135], v[202:205], v[92:95]
	v_mfma_f32_16x16x32_bf16 v[88:91], v[150:153], v[202:205], v[88:91]
	v_mfma_f32_16x16x32_bf16 v[76:79], v[132:135], v[210:213], v[76:79]
	v_mfma_f32_16x16x32_bf16 v[72:75], v[150:153], v[210:213], v[72:75]
	s_setprio 0
	s_setprio 1
	v_mfma_f32_16x16x32_bf16 v[116:119], v[160:163], v[176:179], v[116:119]
	v_mfma_f32_16x16x32_bf16 v[112:115], v[168:171], v[176:179], v[112:115]
	v_mfma_f32_16x16x32_bf16 v[100:103], v[160:163], v[184:187], v[100:103]
	v_mfma_f32_16x16x32_bf16 v[96:99], v[168:171], v[184:187], v[96:99]
	v_mfma_f32_16x16x32_bf16 v[84:87], v[160:163], v[198:201], v[84:87]
	v_mfma_f32_16x16x32_bf16 v[80:83], v[168:171], v[198:201], v[80:83]
	v_mfma_f32_16x16x32_bf16 v[68:71], v[160:163], v[206:209], v[68:71]
	v_mfma_f32_16x16x32_bf16 v[64:67], v[168:171], v[206:209], v[64:67]
	v_mfma_f32_16x16x32_bf16 v[116:119], v[164:167], v[180:183], v[116:119]
	v_mfma_f32_16x16x32_bf16 v[112:115], v[172:175], v[180:183], v[112:115]
	v_mfma_f32_16x16x32_bf16 v[100:103], v[164:167], v[188:191], v[100:103]
	v_mfma_f32_16x16x32_bf16 v[96:99], v[172:175], v[188:191], v[96:99]
	v_mfma_f32_16x16x32_bf16 v[84:87], v[164:167], v[202:205], v[84:87]
	v_mfma_f32_16x16x32_bf16 v[80:83], v[172:175], v[202:205], v[80:83]
	v_mfma_f32_16x16x32_bf16 v[68:71], v[164:167], v[210:213], v[68:71]
	v_mfma_f32_16x16x32_bf16 v[64:67], v[172:175], v[210:213], v[64:67]
	s_setprio 0
	s_barrier
	ds_read_b128 v[176:179], v159 offset:16384
	ds_read_b128 v[180:183], v159 offset:17408
	ds_read_b128 v[184:187], v159 offset:18432
	ds_read_b128 v[188:191], v159 offset:19456
	ds_read_b128 v[198:201], v159 offset:20480
	ds_read_b128 v[202:205], v159 offset:21504
	ds_read_b128 v[206:209], v159 offset:22528
	ds_read_b128 v[210:213], v159 offset:23552
	s_add_u32 s98, s34, 0x80
	s_addc_u32 s99, s35, 0
	s_add_i32 s63, s48, s0
	s_mov_b32 m0, s63
	s_nop 0
	global_load_lds_dwordx4 v196, s[34:35]
	s_add_i32 m0, s63, 0x2000
	s_add_u32 s64, s34, 0x100000
	s_addc_u32 s65, s35, 0
	s_add_i32 s63, s90, s0
	global_load_lds_dwordx4 v136, s[34:35]
	s_mov_b32 m0, s63
	s_nop 0
	global_load_lds_dwordx4 v196, s[64:65]
	s_add_i32 m0, s63, 0x2000
	s_nop 0
	global_load_lds_dwordx4 v136, s[64:65]
	s_waitcnt vmcnt(6)
	s_waitcnt lgkmcnt(0)
	s_barrier
; #define PG8_STAGE(bufoff, gbase, voff) do { _Pragma("unroll") for (int _i = 0; _i < 2; ++_i) \
;         __builtin_amdgcn_global_load_lds((const unsigned*)((const char*)(gbase) + (voff)[_i]), (LAS unsigned*)(lds + (bufoff) + ldsw + _i * 8192), 16, 0, 0); } while (0)
; #define PG8_LDA(dst, b, h) do { _Pragma("unroll") for (int m = 0; m < 4; ++m) _Pragma("unroll") for (int k = 0; k < 2; ++k) dst[m][k] = *(const LAS bf16x8*)(lds + PG8_SA(b, h) + aoff + m * 2048 + k * 1024); } while (0)
; #define PG8_LDB(dst, b, h) do { _Pragma("unroll") for (int n = 0; n < 2; ++n) _Pragma("unroll") for (int k = 0; k < 2; ++k) dst[n][k] = *(const LAS bf16x8*)(lds + PG8_SB(b, h) + boff + n * 2048 + k * 1024); } while (0)
; #define PG8_MMA(ai, bj, At, Bt) do { __builtin_amdgcn_s_setprio(1); _Pragma("unroll") for (int m = 0; m < 4; ++m) _Pragma("unroll") for (int n = 0; n < 2; ++n) _Pragma("unroll") for (int k = 0; k < 2; ++k) \
;         acc[ai][bj][m][n] = __builtin_amdgcn_mfma_f32_16x16x32_bf16(Bt[n][k], At[m][k], acc[ai][bj][m][n], 0, 0, 0); __builtin_amdgcn_s_setprio(0); } while (0)
; #define PG8_WAIT_V(n) asm volatile("s_waitcnt vmcnt(" #n ")" ::: "memory")
; #define PG8_WAIT_L(n) asm volatile("s_waitcnt lgkmcnt(" #n ")" ::: "memory")
; #define PG8_BAR __builtin_amdgcn_s_barrier()
; #define PG8_SCHED __builtin_amdgcn_sched_barrier(0)
; template <class Epi, class Sched, bool ALIGN_EPI = false, bool SP2 = false>
; __device__ __forceinline__ void gemm_phase(LAS unsigned char* lds, const Gemm g, const Sched& S, const Epi& E) {
;     ...
;             PG8_WAIT_V(8); PG8_WAIT_L(0); PG8_BAR; PG8_MMA(1, 0, At, B0); PG8_MMA(1, 1, At, B1); PG8_BAR; PG8_SCHED;
;             PG8_LDB(B0, 1, 0); PG8_LDB(B1, 1, 1); PG8_SCHED; PG8_LDA(At, 1, 0); PG8_STAGE(PG8_SA(0, 1), a2 + hstep, voffA);
;             PG8_WAIT_V(8); PG8_WAIT_L(0); PG8_BAR; PG8_MMA(0, 0, At, B0); PG8_MMA(0, 1, At, B1); PG8_BAR; PG8_SCHED;
	s_setprio 1
	s_waitcnt lgkmcnt(0)
	v_mfma_f32_16x16x32_bf16 v[60:63], v[128:131], v[176:179], v[60:63]
	v_mfma_f32_16x16x32_bf16 v[56:59], v[146:149], v[176:179], v[56:59]
	v_mfma_f32_16x16x32_bf16 v[44:47], v[128:131], v[184:187], v[44:47]
	v_mfma_f32_16x16x32_bf16 v[40:43], v[146:149], v[184:187], v[40:43]
	v_mfma_f32_16x16x32_bf16 v[28:31], v[128:131], v[198:201], v[28:31]
	v_mfma_f32_16x16x32_bf16 v[24:27], v[146:149], v[198:201], v[24:27]
	v_mfma_f32_16x16x32_bf16 v[12:15], v[128:131], v[206:209], v[12:15]
	v_mfma_f32_16x16x32_bf16 v[8:11], v[146:149], v[206:209], v[8:11]
	v_mfma_f32_16x16x32_bf16 v[60:63], v[132:135], v[180:183], v[60:63]
	v_mfma_f32_16x16x32_bf16 v[56:59], v[150:153], v[180:183], v[56:59]
	v_mfma_f32_16x16x32_bf16 v[44:47], v[132:135], v[188:191], v[44:47]
	v_mfma_f32_16x16x32_bf16 v[40:43], v[150:153], v[188:191], v[40:43]
	v_mfma_f32_16x16x32_bf16 v[28:31], v[132:135], v[202:205], v[28:31]
	v_mfma_f32_16x16x32_bf16 v[24:27], v[150:153], v[202:205], v[24:27]
	v_mfma_f32_16x16x32_bf16 v[12:15], v[132:135], v[210:213], v[12:15]
	v_mfma_f32_16x16x32_bf16 v[8:11], v[150:153], v[210:213], v[8:11]
	s_setprio 0
	s_setprio 1
	v_mfma_f32_16x16x32_bf16 v[52:55], v[160:163], v[176:179], v[52:55]
	v_mfma_f32_16x16x32_bf16 v[48:51], v[168:171], v[176:179], v[48:51]
	v_mfma_f32_16x16x32_bf16 v[36:39], v[160:163], v[184:187], v[36:39]
	v_mfma_f32_16x16x32_bf16 v[32:35], v[168:171], v[184:187], v[32:35]
	v_mfma_f32_16x16x32_bf16 v[20:23], v[160:163], v[198:201], v[20:23]
	v_mfma_f32_16x16x32_bf16 v[16:19], v[168:171], v[198:201], v[16:19]
	v_mfma_f32_16x16x32_bf16 v[4:7], v[160:163], v[206:209], v[4:7]
	v_mfma_f32_16x16x32_bf16 v[0:3], v[168:171], v[206:209], v[0:3]
	v_mfma_f32_16x16x32_bf16 v[52:55], v[164:167], v[180:183], v[52:55]
	v_mfma_f32_16x16x32_bf16 v[48:51], v[172:175], v[180:183], v[48:51]
	v_mfma_f32_16x16x32_bf16 v[36:39], v[164:167], v[188:191], v[36:39]
	v_mfma_f32_16x16x32_bf16 v[32:35], v[172:175], v[188:191], v[32:35]
	v_mfma_f32_16x16x32_bf16 v[20:23], v[164:167], v[202:205], v[20:23]
	v_mfma_f32_16x16x32_bf16 v[16:19], v[172:175], v[202:205], v[16:19]
	v_mfma_f32_16x16x32_bf16 v[4:7], v[164:167], v[210:213], v[4:7]
	v_mfma_f32_16x16x32_bf16 v[0:3], v[172:175], v[210:213], v[0:3]
	s_setprio 0
	s_barrier
	v_add_u32_e32 v150, s91, v157
	v_add_u32_e32 v172, s58, v157
	ds_read_b128 v[128:131], v150
	ds_read_b128 v[132:135], v150 offset:1024
	ds_read_b128 v[146:149], v150 offset:2048
	ds_read_b128 v[150:153], v150 offset:3072
	ds_read_b128 v[160:163], v172
	ds_read_b128 v[164:167], v172 offset:1024
	ds_read_b128 v[168:171], v172 offset:2048
	ds_read_b128 v[172:175], v172 offset:3072
	ds_read_b128 v[176:179], v159 offset:32768
	ds_read_b128 v[180:183], v159 offset:33792
	ds_read_b128 v[184:187], v159 offset:34816
	ds_read_b128 v[188:191], v159 offset:35840
	ds_read_b128 v[198:201], v159 offset:36864
	ds_read_b128 v[202:205], v159 offset:37888
	ds_read_b128 v[206:209], v159 offset:38912
	ds_read_b128 v[210:213], v159 offset:39936
	s_mov_b32 m0, s3
	s_nop 0
	global_load_lds_dwordx4 v140, s[36:37]
	s_mov_b32 m0, s17
	s_nop 0
	global_load_lds_dwordx4 v138, s[36:37]
	s_add_u32 s36, s36, 0x100000
	s_addc_u32 s37, s37, 0
	s_mov_b32 m0, s38
	s_nop 0
	global_load_lds_dwordx4 v140, s[36:37]
	s_mov_b32 m0, s39
	s_nop 0
	global_load_lds_dwordx4 v138, s[36:37]
	s_waitcnt vmcnt(8)
	s_waitcnt lgkmcnt(0)
	s_barrier
; #define PG8_STAGE(bufoff, gbase, voff) do { _Pragma("unroll") for (int _i = 0; _i < 2; ++_i) \
;         __builtin_amdgcn_global_load_lds((const unsigned*)((const char*)(gbase) + (voff)[_i]), (LAS unsigned*)(lds + (bufoff) + ldsw + _i * 8192), 16, 0, 0); } while (0)
; #define PG8_LDA(dst, b, h) do { _Pragma("unroll") for (int m = 0; m < 4; ++m) _Pragma("unroll") for (int k = 0; k < 2; ++k) dst[m][k] = *(const LAS bf16x8*)(lds + PG8_SA(b, h) + aoff + m * 2048 + k * 1024); } while (0)
; #define PG8_MMA(ai, bj, At, Bt) do { __builtin_amdgcn_s_setprio(1); _Pragma("unroll") for (int m = 0; m < 4; ++m) _Pragma("unroll") for (int n = 0; n < 2; ++n) _Pragma("unroll") for (int k = 0; k < 2; ++k) \
;         acc[ai][bj][m][n] = __builtin_amdgcn_mfma_f32_16x16x32_bf16(Bt[n][k], At[m][k], acc[ai][bj][m][n], 0, 0, 0); __builtin_amdgcn_s_setprio(0); } while (0)
; #define PG8_WAIT_V(n) asm volatile("s_waitcnt vmcnt(" #n ")" ::: "memory")
; #define PG8_WAIT_L(n) asm volatile("s_waitcnt lgkmcnt(" #n ")" ::: "memory")
; #define PG8_BAR __builtin_amdgcn_s_barrier()
; #define PG8_SCHED __builtin_amdgcn_sched_barrier(0)
; template <class Epi, class Sched, bool ALIGN_EPI = false, bool SP2 = false>
; __device__ __forceinline__ void gemm_phase(LAS unsigned char* lds, const Gemm g, const Sched& S, const Epi& E) {
;     ...
;         for (int t = 0; t < nt; t += 2) {
;     ...
;             PG8_WAIT_V(8); PG8_WAIT_L(0); PG8_BAR; PG8_MMA(0, 0, At, B0); PG8_MMA(0, 1, At, B1); PG8_BAR; PG8_SCHED;
;             PG8_LDA(At, 1, 1); PG8_STAGE(PG8_SB(1, 0), b3, voffB); PG8_STAGE(PG8_SB(1, 1), b3 + hstep, voffB); PG8_STAGE(PG8_SA(1, 0), a3, voffA);
;             PG8_WAIT_V(8); PG8_WAIT_L(0); PG8_BAR; PG8_MMA(1, 0, At, B0); PG8_MMA(1, 1, At, B1); PG8_BAR; PG8_SCHED;
;     ...
;         if constexpr (ALIGN_EPI) { if (wr == 0) PG8_BAR; }
	s_setprio 1
	s_waitcnt lgkmcnt(0)
	v_mfma_f32_16x16x32_bf16 v[124:127], v[128:131], v[176:179], v[124:127]
	v_mfma_f32_16x16x32_bf16 v[120:123], v[146:149], v[176:179], v[120:123]
	v_mfma_f32_16x16x32_bf16 v[108:111], v[128:131], v[184:187], v[108:111]
	v_mfma_f32_16x16x32_bf16 v[104:107], v[146:149], v[184:187], v[104:107]
	v_mfma_f32_16x16x32_bf16 v[92:95], v[128:131], v[198:201], v[92:95]
	v_mfma_f32_16x16x32_bf16 v[88:91], v[146:149], v[198:201], v[88:91]
	v_mfma_f32_16x16x32_bf16 v[76:79], v[128:131], v[206:209], v[76:79]
	v_mfma_f32_16x16x32_bf16 v[72:75], v[146:149], v[206:209], v[72:75]
	v_mfma_f32_16x16x32_bf16 v[124:127], v[132:135], v[180:183], v[124:127]
	v_mfma_f32_16x16x32_bf16 v[120:123], v[150:153], v[180:183], v[120:123]
	v_mfma_f32_16x16x32_bf16 v[108:111], v[132:135], v[188:191], v[108:111]
	v_mfma_f32_16x16x32_bf16 v[104:107], v[150:153], v[188:191], v[104:107]
	v_mfma_f32_16x16x32_bf16 v[92:95], v[132:135], v[202:205], v[92:95]
	v_mfma_f32_16x16x32_bf16 v[88:91], v[150:153], v[202:205], v[88:91]
	v_mfma_f32_16x16x32_bf16 v[76:79], v[132:135], v[210:213], v[76:79]
	v_mfma_f32_16x16x32_bf16 v[72:75], v[150:153], v[210:213], v[72:75]
	s_setprio 0
	s_setprio 1
	v_mfma_f32_16x16x32_bf16 v[116:119], v[160:163], v[176:179], v[116:119]
	v_mfma_f32_16x16x32_bf16 v[112:115], v[168:171], v[176:179], v[112:115]
	v_mfma_f32_16x16x32_bf16 v[100:103], v[160:163], v[184:187], v[100:103]
	v_mfma_f32_16x16x32_bf16 v[96:99], v[168:171], v[184:187], v[96:99]
	v_mfma_f32_16x16x32_bf16 v[84:87], v[160:163], v[198:201], v[84:87]
	v_mfma_f32_16x16x32_bf16 v[80:83], v[168:171], v[198:201], v[80:83]
	v_mfma_f32_16x16x32_bf16 v[68:71], v[160:163], v[206:209], v[68:71]
	v_mfma_f32_16x16x32_bf16 v[64:67], v[168:171], v[206:209], v[64:67]
	v_mfma_f32_16x16x32_bf16 v[116:119], v[164:167], v[180:183], v[116:119]
	v_mfma_f32_16x16x32_bf16 v[112:115], v[172:175], v[180:183], v[112:115]
	v_mfma_f32_16x16x32_bf16 v[100:103], v[164:167], v[188:191], v[100:103]
	v_mfma_f32_16x16x32_bf16 v[96:99], v[172:175], v[188:191], v[96:99]
	v_mfma_f32_16x16x32_bf16 v[84:87], v[164:167], v[202:205], v[84:87]
	v_mfma_f32_16x16x32_bf16 v[80:83], v[172:175], v[202:205], v[80:83]
	v_mfma_f32_16x16x32_bf16 v[68:71], v[164:167], v[210:213], v[68:71]
	v_mfma_f32_16x16x32_bf16 v[64:67], v[172:175], v[210:213], v[64:67]
	s_setprio 0
	s_barrier
	ds_read_b128 v[176:179], v159 offset:49152
	ds_read_b128 v[180:183], v159 offset:50176
	ds_read_b128 v[184:187], v159 offset:51200
	ds_read_b128 v[188:191], v159 offset:52224
	ds_read_b128 v[198:201], v159 offset:53248
	ds_read_b128 v[202:205], v159 offset:54272
	ds_read_b128 v[206:209], v159 offset:55296
	ds_read_b128 v[210:213], v159 offset:56320
	s_add_i32 s36, s91, s0
	s_mov_b32 m0, s36
	s_nop 0
	global_load_lds_dwordx4 v196, s[98:99]
	s_add_i32 m0, s36, 0x2000
	s_add_u32 s34, s34, 0x100080
	s_addc_u32 s35, s35, 0
	s_add_i32 s36, s58, s0
	global_load_lds_dwordx4 v136, s[98:99]
	s_mov_b32 m0, s36
	s_nop 0
	global_load_lds_dwordx4 v196, s[34:35]
	s_add_i32 m0, s36, 0x2000
	s_nop 0
	global_load_lds_dwordx4 v136, s[34:35]
	s_nop 0
	s_waitcnt vmcnt(6)
	s_waitcnt lgkmcnt(0)
	s_barrier
	s_setprio 1
	s_waitcnt lgkmcnt(0)
	v_mfma_f32_16x16x32_bf16 v[60:63], v[128:131], v[176:179], v[60:63]
	v_mfma_f32_16x16x32_bf16 v[56:59], v[146:149], v[176:179], v[56:59]
	v_mfma_f32_16x16x32_bf16 v[44:47], v[128:131], v[184:187], v[44:47]
	v_mfma_f32_16x16x32_bf16 v[40:43], v[146:149], v[184:187], v[40:43]
	v_mfma_f32_16x16x32_bf16 v[28:31], v[128:131], v[198:201], v[28:31]
	v_mfma_f32_16x16x32_bf16 v[24:27], v[146:149], v[198:201], v[24:27]
	v_mfma_f32_16x16x32_bf16 v[12:15], v[128:131], v[206:209], v[12:15]
	v_mfma_f32_16x16x32_bf16 v[8:11], v[146:149], v[206:209], v[8:11]
	v_mfma_f32_16x16x32_bf16 v[60:63], v[132:135], v[180:183], v[60:63]
	v_mfma_f32_16x16x32_bf16 v[56:59], v[150:153], v[180:183], v[56:59]
	v_mfma_f32_16x16x32_bf16 v[44:47], v[132:135], v[188:191], v[44:47]
	v_mfma_f32_16x16x32_bf16 v[40:43], v[150:153], v[188:191], v[40:43]
	v_mfma_f32_16x16x32_bf16 v[28:31], v[132:135], v[202:205], v[28:31]
	v_mfma_f32_16x16x32_bf16 v[24:27], v[150:153], v[202:205], v[24:27]
	v_mfma_f32_16x16x32_bf16 v[12:15], v[132:135], v[210:213], v[12:15]
	v_mfma_f32_16x16x32_bf16 v[8:11], v[150:153], v[210:213], v[8:11]
	s_setprio 0
	s_setprio 1
	v_mfma_f32_16x16x32_bf16 v[52:55], v[160:163], v[176:179], v[52:55]
	v_mfma_f32_16x16x32_bf16 v[48:51], v[168:171], v[176:179], v[48:51]
	v_mfma_f32_16x16x32_bf16 v[36:39], v[160:163], v[184:187], v[36:39]
	v_mfma_f32_16x16x32_bf16 v[32:35], v[168:171], v[184:187], v[32:35]
	v_mfma_f32_16x16x32_bf16 v[20:23], v[160:163], v[198:201], v[20:23]
	v_mfma_f32_16x16x32_bf16 v[16:19], v[168:171], v[198:201], v[16:19]
	v_mfma_f32_16x16x32_bf16 v[4:7], v[160:163], v[206:209], v[4:7]
	v_mfma_f32_16x16x32_bf16 v[0:3], v[168:171], v[206:209], v[0:3]
	v_mfma_f32_16x16x32_bf16 v[52:55], v[164:167], v[180:183], v[52:55]
	v_mfma_f32_16x16x32_bf16 v[48:51], v[172:175], v[180:183], v[48:51]
	v_mfma_f32_16x16x32_bf16 v[36:39], v[164:167], v[188:191], v[36:39]
	v_mfma_f32_16x16x32_bf16 v[32:35], v[172:175], v[188:191], v[32:35]
	v_mfma_f32_16x16x32_bf16 v[20:23], v[164:167], v[202:205], v[20:23]
	v_mfma_f32_16x16x32_bf16 v[16:19], v[172:175], v[202:205], v[16:19]
	v_mfma_f32_16x16x32_bf16 v[4:7], v[164:167], v[210:213], v[4:7]
	v_mfma_f32_16x16x32_bf16 v[0:3], v[172:175], v[210:213], v[0:3]
	s_setprio 0
	s_barrier
	s_add_i32 s62, s62, 2
	s_add_u32 s10, s10, 0x100
	s_addc_u32 s11, s11, 0
	s_add_u32 s54, s54, 0x100
	s_addc_u32 s59, s59, 0
	s_cmp_gt_u32 s62, 61
	s_cbranch_scc0 .LBB0_832
	s_nop 0
	s_and_b64 vcc, exec, s[20:21]
	s_cbranch_vccz .LBB0_835
	s_barrier
